# nt streaming hint on P1's 36 dwordx4 stores (weight-transpose outputs consumed phases later), on top of nt P0/P1 input loads and nt final output stores
# speedup vs baseline: 1.0221x; 1.0028x over previous
; __device__ __forceinline__ unsigned cvt_pk_bf16(float lo, float hi) { f32x2c_t v = {lo, hi}; bf16x2c_t b = __builtin_convertvector(v, bf16x2c_t); return __builtin_bit_cast(unsigned, b); }
; __device__ __forceinline__ float bf_lo(unsigned w) { return __uint_as_float(w << 16); }
; __device__ __forceinline__ float bf_hi(unsigned w) { return __uint_as_float(w & 0xffff0000u); }
;     __device__ __forceinline__ void operator()(const f32x4 (&acc)[2][2][4][2], const Unit& u, int wr, int wc, int fr, int fq) const {
;     ...
;             for (int m = 0; m < 4; ++m) { bf16_t* rowp = O + (size_t)(row0 + ai * HALF + m * 16) * ldc + col0;
; #pragma unroll
;                 for (int bj = 0; bj < 2; ++bj) { const f32x4 v0 = acc[ai][bj][m][0] + 0.f, v1 = acc[ai][bj][m][1] + 0.f;
;                     u32x4 w; w.x = cvt_pk_bf16(v0[0], v0[1]); w.y = cvt_pk_bf16(v0[2], v0[3]); w.z = cvt_pk_bf16(v1[0], v1[1]); w.w = cvt_pk_bf16(v1[2], v1[3]);
;                     *(u32x4*)(rowp + bj * HALF) = w;
;                     if (isk) { float q = (bf_lo(w.x) * bf_lo(w.x) + bf_hi(w.x) * bf_hi(w.x)) + (bf_lo(w.y) * bf_lo(w.y) + bf_hi(w.y) * bf_hi(w.y))
;                                        + (bf_lo(w.z) * bf_lo(w.z) + bf_hi(w.z) * bf_hi(w.z)) + (bf_lo(w.w) * bf_lo(w.w) + bf_hi(w.w) * bf_hi(w.w));
;                         q += __shfl_xor(q, 16); q += __shfl_xor(q, 32); kmx[bj] = fmaxf(kmx[bj], q); } } }
.LBB0_153:
	s_and_b32 s4, s30, -4
	v_lshl_or_b32 v146, s30, 8, v160
	s_cmp_eq_u32 s4, 4
	v_lshl_add_u32 v165, s34, 8, v158
	v_mov_b64_e32 v[148:149], s[78:79]
	s_cselect_b64 s[50:51], -1, 0
	s_cmp_lg_u32 s4, 4
	v_ashrrev_i32_e32 v147, 31, v146
	v_mad_i64_i32 v[148:149], s[4:5], v165, s76, v[148:149]
	v_pk_add_f32 v[126:127], v[126:127], 0 op_sel_hi:[1,0]
	v_pk_add_f32 v[124:125], v[124:125], 0 op_sel_hi:[1,0]
	v_pk_add_f32 v[166:167], v[122:123], 0 op_sel_hi:[1,0]
	v_pk_add_f32 v[122:123], v[120:121], 0 op_sel_hi:[1,0]
	v_lshl_add_u64 v[148:149], v[146:147], 1, v[148:149]
	v_cvt_pk_bf16_f32 v120, v124, v125
	v_cvt_pk_bf16_f32 v121, v126, v127
	v_cvt_pk_bf16_f32 v122, v122, v123
	v_cvt_pk_bf16_f32 v123, v166, v167
	global_store_dwordx4 v[148:149], v[120:123], off nt
	s_cbranch_scc1 .LBB0_155
	v_lshlrev_b32_e32 v125, 16, v121
	v_lshlrev_b32_e32 v124, 16, v120
	v_and_b32_e32 v121, 0xffff0000, v121
	v_and_b32_e32 v120, 0xffff0000, v120
	v_pk_mul_f32 v[120:121], v[120:121], v[120:121]
	v_and_b32_e32 v127, 0xffff0000, v122
	v_and_b32_e32 v126, 0xffff0000, v123
	v_pk_fma_f32 v[120:121], v[124:125], v[124:125], v[120:121]
	v_lshlrev_b32_e32 v125, 16, v122
	v_lshlrev_b32_e32 v124, 16, v123
	v_pk_mul_f32 v[122:123], v[126:127], v[126:127]
	v_add_f32_e32 v120, v120, v121
	v_pk_fma_f32 v[122:123], v[124:125], v[124:125], v[122:123]
	v_xor_b32_e32 v121, 16, v164
	v_add_f32_e32 v120, v120, v123
	v_add_f32_e32 v120, v122, v120
	v_and_b32_e32 v122, 64, v164
	v_add_u32_e32 v122, 64, v122
	v_cmp_lt_i32_e32 vcc, v121, v122
	s_nop 1
	v_cndmask_b32_e32 v121, v164, v121, vcc
	v_lshlrev_b32_e32 v121, 2, v121
	ds_bpermute_b32 v121, v121, v120
	s_waitcnt lgkmcnt(0)
	v_add_f32_e32 v120, v120, v121
	v_xor_b32_e32 v121, 32, v164
	v_cmp_lt_i32_e32 vcc, v121, v122
	s_nop 1
	v_cndmask_b32_e32 v121, v164, v121, vcc
	v_lshlrev_b32_e32 v121, 2, v121
	ds_bpermute_b32 v121, v121, v120
	s_waitcnt lgkmcnt(0)
	v_add_f32_e32 v120, v120, v121
	v_max_f32_e32 v120, 0, v120
	v_mov_b32_e32 v121, v136
	s_branch .LBB0_156

; __device__ __forceinline__ unsigned cvt_pk_bf16(float lo, float hi) { f32x2c_t v = {lo, hi}; bf16x2c_t b = __builtin_convertvector(v, bf16x2c_t); return __builtin_bit_cast(unsigned, b); }
; __device__ __forceinline__ float bf_lo(unsigned w) { return __uint_as_float(w << 16); }
; __device__ __forceinline__ float bf_hi(unsigned w) { return __uint_as_float(w & 0xffff0000u); }
;     __device__ __forceinline__ void operator()(const f32x4 (&acc)[2][2][4][2], const Unit& u, int wr, int wc, int fr, int fq) const {
;     ...
;             for (int m = 0; m < 4; ++m) { bf16_t* rowp = O + (size_t)(row0 + ai * HALF + m * 16) * ldc + col0;
; #pragma unroll
;                 for (int bj = 0; bj < 2; ++bj) { const f32x4 v0 = acc[ai][bj][m][0] + 0.f, v1 = acc[ai][bj][m][1] + 0.f;
;                     u32x4 w; w.x = cvt_pk_bf16(v0[0], v0[1]); w.y = cvt_pk_bf16(v0[2], v0[3]); w.z = cvt_pk_bf16(v1[0], v1[1]); w.w = cvt_pk_bf16(v1[2], v1[3]);
;                     *(u32x4*)(rowp + bj * HALF) = w;
;                     if (isk) { float q = (bf_lo(w.x) * bf_lo(w.x) + bf_hi(w.x) * bf_hi(w.x)) + (bf_lo(w.y) * bf_lo(w.y) + bf_hi(w.y) * bf_hi(w.y))
;                                        + (bf_lo(w.z) * bf_lo(w.z) + bf_hi(w.z) * bf_hi(w.z)) + (bf_lo(w.w) * bf_lo(w.w) + bf_hi(w.w) * bf_hi(w.w));
;                         q += __shfl_xor(q, 16); q += __shfl_xor(q, 32); kmx[bj] = fmaxf(kmx[bj], q); } } }
.LBB0_156:
	v_pk_add_f32 v[116:117], v[116:117], 0 op_sel_hi:[1,0]
	v_pk_add_f32 v[118:119], v[118:119], 0 op_sel_hi:[1,0]
	v_pk_add_f32 v[122:123], v[114:115], 0 op_sel_hi:[1,0]
	v_pk_add_f32 v[114:115], v[112:113], 0 op_sel_hi:[1,0]
	v_cvt_pk_bf16_f32 v112, v116, v117
	v_cndmask_b32_e64 v116, 0, 1, s[50:51]
	v_cvt_pk_bf16_f32 v113, v118, v119
	v_cvt_pk_bf16_f32 v114, v114, v115
	v_cvt_pk_bf16_f32 v115, v122, v123
	v_cmp_ne_u32_e64 s[4:5], 1, v116
	s_andn2_b64 vcc, exec, s[50:51]
	global_store_dwordx4 v[148:149], v[112:115], off offset:256 nt
	s_cbranch_vccnz .LBB0_158
	v_lshlrev_b32_e32 v117, 16, v113
	v_lshlrev_b32_e32 v116, 16, v112
	v_and_b32_e32 v113, 0xffff0000, v113
	v_and_b32_e32 v112, 0xffff0000, v112
	v_pk_mul_f32 v[112:113], v[112:113], v[112:113]
	v_and_b32_e32 v119, 0xffff0000, v114
	v_and_b32_e32 v118, 0xffff0000, v115
	v_pk_fma_f32 v[112:113], v[116:117], v[116:117], v[112:113]
	v_lshlrev_b32_e32 v117, 16, v114
	v_lshlrev_b32_e32 v116, 16, v115
	v_pk_mul_f32 v[114:115], v[118:119], v[118:119]
	v_add_f32_e32 v112, v112, v113
	v_pk_fma_f32 v[114:115], v[116:117], v[116:117], v[114:115]
	v_xor_b32_e32 v113, 16, v164
	v_add_f32_e32 v112, v112, v115
	v_add_f32_e32 v112, v114, v112
	v_and_b32_e32 v114, 64, v164
	v_add_u32_e32 v114, 64, v114
	v_cmp_lt_i32_e32 vcc, v113, v114
	s_nop 1
	v_cndmask_b32_e32 v113, v164, v113, vcc
	v_lshlrev_b32_e32 v113, 2, v113
	ds_bpermute_b32 v113, v113, v112
	s_waitcnt lgkmcnt(0)
	v_add_f32_e32 v112, v112, v113
	v_xor_b32_e32 v113, 32, v164
	v_cmp_lt_i32_e32 vcc, v113, v114
	s_nop 1
	v_cndmask_b32_e32 v113, v164, v113, vcc
	v_lshlrev_b32_e32 v113, 2, v113
	ds_bpermute_b32 v113, v113, v112
	s_waitcnt lgkmcnt(0)
	v_add_f32_e32 v112, v112, v113
	v_max_f32_e32 v113, v121, v121
	v_max_f32_e32 v121, v113, v112
.LBB0_158:
	s_nop 0
	v_or_b32_e32 v114, 16, v165
	v_mov_b64_e32 v[112:113], s[78:79]
	v_mad_i64_i32 v[112:113], s[50:51], v114, s76, v[112:113]
	v_pk_add_f32 v[110:111], v[110:111], 0 op_sel_hi:[1,0]
	v_pk_add_f32 v[108:109], v[108:109], 0 op_sel_hi:[1,0]
	v_pk_add_f32 v[114:115], v[106:107], 0 op_sel_hi:[1,0]
	v_pk_add_f32 v[106:107], v[104:105], 0 op_sel_hi:[1,0]
	v_lshl_add_u64 v[112:113], v[146:147], 1, v[112:113]
	v_cvt_pk_bf16_f32 v104, v108, v109
	v_cvt_pk_bf16_f32 v105, v110, v111
	v_cvt_pk_bf16_f32 v106, v106, v107
	v_cvt_pk_bf16_f32 v107, v114, v115
	s_and_b64 vcc, exec, s[4:5]
	global_store_dwordx4 v[112:113], v[104:107], off nt
	s_cbranch_vccnz .LBB0_160
	v_lshlrev_b32_e32 v109, 16, v105
	v_lshlrev_b32_e32 v108, 16, v104
	v_and_b32_e32 v105, 0xffff0000, v105
	v_and_b32_e32 v104, 0xffff0000, v104
	v_pk_mul_f32 v[104:105], v[104:105], v[104:105]
	v_and_b32_e32 v111, 0xffff0000, v106
	v_and_b32_e32 v110, 0xffff0000, v107
	v_pk_fma_f32 v[104:105], v[108:109], v[108:109], v[104:105]
	v_lshlrev_b32_e32 v109, 16, v106
	v_lshlrev_b32_e32 v108, 16, v107
	v_pk_mul_f32 v[106:107], v[110:111], v[110:111]
	v_add_f32_e32 v104, v104, v105
	v_pk_fma_f32 v[106:107], v[108:109], v[108:109], v[106:107]
	v_xor_b32_e32 v105, 16, v164
	v_add_f32_e32 v104, v104, v107
	v_add_f32_e32 v104, v106, v104
	v_and_b32_e32 v106, 64, v164
	v_add_u32_e32 v106, 64, v106
	v_cmp_lt_i32_e32 vcc, v105, v106
	s_nop 1
	v_cndmask_b32_e32 v105, v164, v105, vcc
	v_lshlrev_b32_e32 v105, 2, v105
	ds_bpermute_b32 v105, v105, v104
	s_waitcnt lgkmcnt(0)
	v_add_f32_e32 v104, v104, v105
	v_xor_b32_e32 v105, 32, v164
	v_cmp_lt_i32_e32 vcc, v105, v106
	s_nop 1
	v_cndmask_b32_e32 v105, v164, v105, vcc
	v_lshlrev_b32_e32 v105, 2, v105
	ds_bpermute_b32 v105, v105, v104
	s_waitcnt lgkmcnt(0)
	v_add_f32_e32 v104, v104, v105
	v_max_f32_e32 v105, v120, v120
	v_max_f32_e32 v120, v105, v104
.LBB0_160:
	v_pk_add_f32 v[102:103], v[102:103], 0 op_sel_hi:[1,0]
	v_pk_add_f32 v[100:101], v[100:101], 0 op_sel_hi:[1,0]
	v_pk_add_f32 v[104:105], v[98:99], 0 op_sel_hi:[1,0]
	v_pk_add_f32 v[98:99], v[96:97], 0 op_sel_hi:[1,0]
	v_cvt_pk_bf16_f32 v96, v100, v101
	v_cvt_pk_bf16_f32 v97, v102, v103
	v_cvt_pk_bf16_f32 v98, v98, v99
	v_cvt_pk_bf16_f32 v99, v104, v105
	s_and_b64 vcc, exec, s[4:5]
	global_store_dwordx4 v[112:113], v[96:99], off offset:256 nt
	s_cbranch_vccnz .LBB0_162
	v_lshlrev_b32_e32 v101, 16, v97
	v_lshlrev_b32_e32 v100, 16, v96
	v_and_b32_e32 v97, 0xffff0000, v97
	v_and_b32_e32 v96, 0xffff0000, v96
	v_pk_mul_f32 v[96:97], v[96:97], v[96:97]
	v_and_b32_e32 v103, 0xffff0000, v98
	v_and_b32_e32 v102, 0xffff0000, v99
	v_pk_fma_f32 v[96:97], v[100:101], v[100:101], v[96:97]
	v_lshlrev_b32_e32 v101, 16, v98
	v_lshlrev_b32_e32 v100, 16, v99
	v_pk_mul_f32 v[98:99], v[102:103], v[102:103]
	v_add_f32_e32 v96, v96, v97
	v_pk_fma_f32 v[98:99], v[100:101], v[100:101], v[98:99]
	v_xor_b32_e32 v97, 16, v164
	v_add_f32_e32 v96, v96, v99
	v_add_f32_e32 v96, v98, v96
	v_and_b32_e32 v98, 64, v164
	v_add_u32_e32 v98, 64, v98
	v_cmp_lt_i32_e32 vcc, v97, v98
	s_nop 1
	v_cndmask_b32_e32 v97, v164, v97, vcc
	v_lshlrev_b32_e32 v97, 2, v97
	ds_bpermute_b32 v97, v97, v96
	s_waitcnt lgkmcnt(0)
	v_add_f32_e32 v96, v96, v97
	v_xor_b32_e32 v97, 32, v164
	v_cmp_lt_i32_e32 vcc, v97, v98
	s_nop 1
	v_cndmask_b32_e32 v97, v164, v97, vcc
	v_lshlrev_b32_e32 v97, 2, v97
	ds_bpermute_b32 v97, v97, v96
	s_waitcnt lgkmcnt(0)
	v_add_f32_e32 v96, v96, v97
	v_max_f32_e32 v97, v121, v121
	v_max_f32_e32 v121, v97, v96
; __device__ __forceinline__ unsigned cvt_pk_bf16(float lo, float hi) { f32x2c_t v = {lo, hi}; bf16x2c_t b = __builtin_convertvector(v, bf16x2c_t); return __builtin_bit_cast(unsigned, b); }
; __device__ __forceinline__ float bf_lo(unsigned w) { return __uint_as_float(w << 16); }
; __device__ __forceinline__ float bf_hi(unsigned w) { return __uint_as_float(w & 0xffff0000u); }
;     __device__ __forceinline__ void operator()(const f32x4 (&acc)[2][2][4][2], const Unit& u, int wr, int wc, int fr, int fq) const {
;     ...
;             for (int m = 0; m < 4; ++m) { bf16_t* rowp = O + (size_t)(row0 + ai * HALF + m * 16) * ldc + col0;
; #pragma unroll
;                 for (int bj = 0; bj < 2; ++bj) { const f32x4 v0 = acc[ai][bj][m][0] + 0.f, v1 = acc[ai][bj][m][1] + 0.f;
;                     u32x4 w; w.x = cvt_pk_bf16(v0[0], v0[1]); w.y = cvt_pk_bf16(v0[2], v0[3]); w.z = cvt_pk_bf16(v1[0], v1[1]); w.w = cvt_pk_bf16(v1[2], v1[3]);
;                     *(u32x4*)(rowp + bj * HALF) = w;
;                     if (isk) { float q = (bf_lo(w.x) * bf_lo(w.x) + bf_hi(w.x) * bf_hi(w.x)) + (bf_lo(w.y) * bf_lo(w.y) + bf_hi(w.y) * bf_hi(w.y))
;                                        + (bf_lo(w.z) * bf_lo(w.z) + bf_hi(w.z) * bf_hi(w.z)) + (bf_lo(w.w) * bf_lo(w.w) + bf_hi(w.w) * bf_hi(w.w));
;                         q += __shfl_xor(q, 16); q += __shfl_xor(q, 32); kmx[bj] = fmaxf(kmx[bj], q); } } }
.LBB0_162:
	s_nop 0
	v_or_b32_e32 v98, 32, v165
	v_mov_b64_e32 v[96:97], s[78:79]
	v_mad_i64_i32 v[96:97], s[50:51], v98, s76, v[96:97]
	v_pk_add_f32 v[94:95], v[94:95], 0 op_sel_hi:[1,0]
	v_pk_add_f32 v[92:93], v[92:93], 0 op_sel_hi:[1,0]
	v_pk_add_f32 v[98:99], v[90:91], 0 op_sel_hi:[1,0]
	v_pk_add_f32 v[90:91], v[88:89], 0 op_sel_hi:[1,0]
	v_lshl_add_u64 v[96:97], v[146:147], 1, v[96:97]
	v_cvt_pk_bf16_f32 v88, v92, v93
	v_cvt_pk_bf16_f32 v89, v94, v95
	v_cvt_pk_bf16_f32 v90, v90, v91
	v_cvt_pk_bf16_f32 v91, v98, v99
	s_and_b64 vcc, exec, s[4:5]
	global_store_dwordx4 v[96:97], v[88:91], off nt
	s_cbranch_vccnz .LBB0_164
	v_lshlrev_b32_e32 v93, 16, v89
	v_lshlrev_b32_e32 v92, 16, v88
	v_and_b32_e32 v89, 0xffff0000, v89
	v_and_b32_e32 v88, 0xffff0000, v88
	v_pk_mul_f32 v[88:89], v[88:89], v[88:89]
	v_and_b32_e32 v95, 0xffff0000, v90
	v_and_b32_e32 v94, 0xffff0000, v91
	v_pk_fma_f32 v[88:89], v[92:93], v[92:93], v[88:89]
	v_lshlrev_b32_e32 v93, 16, v90
	v_lshlrev_b32_e32 v92, 16, v91
	v_pk_mul_f32 v[90:91], v[94:95], v[94:95]
	v_add_f32_e32 v88, v88, v89
	v_pk_fma_f32 v[90:91], v[92:93], v[92:93], v[90:91]
	v_xor_b32_e32 v89, 16, v164
	v_add_f32_e32 v88, v88, v91
	v_add_f32_e32 v88, v90, v88
	v_and_b32_e32 v90, 64, v164
	v_add_u32_e32 v90, 64, v90
	v_cmp_lt_i32_e32 vcc, v89, v90
	s_nop 1
	v_cndmask_b32_e32 v89, v164, v89, vcc
	v_lshlrev_b32_e32 v89, 2, v89
	ds_bpermute_b32 v89, v89, v88
	s_waitcnt lgkmcnt(0)
	v_add_f32_e32 v88, v88, v89
	v_xor_b32_e32 v89, 32, v164
	v_cmp_lt_i32_e32 vcc, v89, v90
	s_nop 1
	v_cndmask_b32_e32 v89, v164, v89, vcc
	v_lshlrev_b32_e32 v89, 2, v89
	ds_bpermute_b32 v89, v89, v88
	s_waitcnt lgkmcnt(0)
	v_add_f32_e32 v88, v88, v89
	v_max_f32_e32 v89, v120, v120
	v_max_f32_e32 v120, v89, v88
.LBB0_164:
	v_pk_add_f32 v[86:87], v[86:87], 0 op_sel_hi:[1,0]
	v_pk_add_f32 v[84:85], v[84:85], 0 op_sel_hi:[1,0]
	v_pk_add_f32 v[88:89], v[82:83], 0 op_sel_hi:[1,0]
	v_pk_add_f32 v[82:83], v[80:81], 0 op_sel_hi:[1,0]
	v_cvt_pk_bf16_f32 v80, v84, v85
	v_cvt_pk_bf16_f32 v81, v86, v87
	v_cvt_pk_bf16_f32 v82, v82, v83
	v_cvt_pk_bf16_f32 v83, v88, v89
	s_and_b64 vcc, exec, s[4:5]
	global_store_dwordx4 v[96:97], v[80:83], off offset:256 nt
	s_cbranch_vccnz .LBB0_166
	v_lshlrev_b32_e32 v85, 16, v81
	v_lshlrev_b32_e32 v84, 16, v80
	v_and_b32_e32 v81, 0xffff0000, v81
	v_and_b32_e32 v80, 0xffff0000, v80
	v_pk_mul_f32 v[80:81], v[80:81], v[80:81]
	v_and_b32_e32 v87, 0xffff0000, v82
	v_and_b32_e32 v86, 0xffff0000, v83
	v_pk_fma_f32 v[80:81], v[84:85], v[84:85], v[80:81]
	v_lshlrev_b32_e32 v85, 16, v82
	v_lshlrev_b32_e32 v84, 16, v83
	v_pk_mul_f32 v[82:83], v[86:87], v[86:87]
	v_add_f32_e32 v80, v80, v81
	v_pk_fma_f32 v[82:83], v[84:85], v[84:85], v[82:83]
	v_xor_b32_e32 v81, 16, v164
	v_add_f32_e32 v80, v80, v83
	v_add_f32_e32 v80, v82, v80
	v_and_b32_e32 v82, 64, v164
	v_add_u32_e32 v82, 64, v82
	v_cmp_lt_i32_e32 vcc, v81, v82
	s_nop 1
	v_cndmask_b32_e32 v81, v164, v81, vcc
	v_lshlrev_b32_e32 v81, 2, v81
	ds_bpermute_b32 v81, v81, v80
	s_waitcnt lgkmcnt(0)
	v_add_f32_e32 v80, v80, v81
	v_xor_b32_e32 v81, 32, v164
	v_cmp_lt_i32_e32 vcc, v81, v82
	s_nop 1
	v_cndmask_b32_e32 v81, v164, v81, vcc
	v_lshlrev_b32_e32 v81, 2, v81
	ds_bpermute_b32 v81, v81, v80
	s_waitcnt lgkmcnt(0)
	v_add_f32_e32 v80, v80, v81
	v_max_f32_e32 v81, v121, v121
	v_max_f32_e32 v121, v81, v80
.LBB0_166:
	s_nop 0
	v_or_b32_e32 v82, 48, v165
	v_mov_b64_e32 v[80:81], s[78:79]
	v_mad_i64_i32 v[80:81], s[50:51], v82, s76, v[80:81]
	v_pk_add_f32 v[78:79], v[78:79], 0 op_sel_hi:[1,0]
	v_pk_add_f32 v[76:77], v[76:77], 0 op_sel_hi:[1,0]
	v_pk_add_f32 v[82:83], v[74:75], 0 op_sel_hi:[1,0]
	v_pk_add_f32 v[74:75], v[72:73], 0 op_sel_hi:[1,0]
	v_lshl_add_u64 v[80:81], v[146:147], 1, v[80:81]
	v_cvt_pk_bf16_f32 v72, v76, v77
	v_cvt_pk_bf16_f32 v73, v78, v79
	v_cvt_pk_bf16_f32 v74, v74, v75
	v_cvt_pk_bf16_f32 v75, v82, v83
	s_and_b64 vcc, exec, s[4:5]
	global_store_dwordx4 v[80:81], v[72:75], off nt
	s_cbranch_vccnz .LBB0_168
	v_lshlrev_b32_e32 v77, 16, v73
	v_lshlrev_b32_e32 v76, 16, v72
	v_and_b32_e32 v73, 0xffff0000, v73
	v_and_b32_e32 v72, 0xffff0000, v72
	v_pk_mul_f32 v[72:73], v[72:73], v[72:73]
	v_and_b32_e32 v79, 0xffff0000, v74
	v_and_b32_e32 v78, 0xffff0000, v75
	v_pk_fma_f32 v[72:73], v[76:77], v[76:77], v[72:73]
	v_lshlrev_b32_e32 v77, 16, v74
	v_lshlrev_b32_e32 v76, 16, v75
	v_pk_mul_f32 v[74:75], v[78:79], v[78:79]
	v_add_f32_e32 v72, v72, v73
	v_pk_fma_f32 v[74:75], v[76:77], v[76:77], v[74:75]
	v_xor_b32_e32 v73, 16, v164
	v_add_f32_e32 v72, v72, v75
	v_add_f32_e32 v72, v74, v72
	v_and_b32_e32 v74, 64, v164
	v_add_u32_e32 v74, 64, v74
	v_cmp_lt_i32_e32 vcc, v73, v74
	s_nop 1
	v_cndmask_b32_e32 v73, v164, v73, vcc
	v_lshlrev_b32_e32 v73, 2, v73
	ds_bpermute_b32 v73, v73, v72
	s_waitcnt lgkmcnt(0)
	v_add_f32_e32 v72, v72, v73
	v_xor_b32_e32 v73, 32, v164
	v_cmp_lt_i32_e32 vcc, v73, v74
	s_nop 1
	v_cndmask_b32_e32 v73, v164, v73, vcc
	v_lshlrev_b32_e32 v73, 2, v73
	ds_bpermute_b32 v73, v73, v72
	s_waitcnt lgkmcnt(0)
	v_add_f32_e32 v72, v72, v73
	v_max_f32_e32 v73, v120, v120
	v_max_f32_e32 v120, v73, v72
; __device__ __forceinline__ unsigned cvt_pk_bf16(float lo, float hi) { f32x2c_t v = {lo, hi}; bf16x2c_t b = __builtin_convertvector(v, bf16x2c_t); return __builtin_bit_cast(unsigned, b); }
; __device__ __forceinline__ float bf_lo(unsigned w) { return __uint_as_float(w << 16); }
; __device__ __forceinline__ float bf_hi(unsigned w) { return __uint_as_float(w & 0xffff0000u); }
;     __device__ __forceinline__ void operator()(const f32x4 (&acc)[2][2][4][2], const Unit& u, int wr, int wc, int fr, int fq) const {
;     ...
;             for (int m = 0; m < 4; ++m) { bf16_t* rowp = O + (size_t)(row0 + ai * HALF + m * 16) * ldc + col0;
; #pragma unroll
;                 for (int bj = 0; bj < 2; ++bj) { const f32x4 v0 = acc[ai][bj][m][0] + 0.f, v1 = acc[ai][bj][m][1] + 0.f;
;                     u32x4 w; w.x = cvt_pk_bf16(v0[0], v0[1]); w.y = cvt_pk_bf16(v0[2], v0[3]); w.z = cvt_pk_bf16(v1[0], v1[1]); w.w = cvt_pk_bf16(v1[2], v1[3]);
;                     *(u32x4*)(rowp + bj * HALF) = w;
;                     if (isk) { float q = (bf_lo(w.x) * bf_lo(w.x) + bf_hi(w.x) * bf_hi(w.x)) + (bf_lo(w.y) * bf_lo(w.y) + bf_hi(w.y) * bf_hi(w.y))
;                                        + (bf_lo(w.z) * bf_lo(w.z) + bf_hi(w.z) * bf_hi(w.z)) + (bf_lo(w.w) * bf_lo(w.w) + bf_hi(w.w) * bf_hi(w.w));
;                         q += __shfl_xor(q, 16); q += __shfl_xor(q, 32); kmx[bj] = fmaxf(kmx[bj], q); } } }
.LBB0_168:
	v_pk_add_f32 v[70:71], v[70:71], 0 op_sel_hi:[1,0]
	v_pk_add_f32 v[68:69], v[68:69], 0 op_sel_hi:[1,0]
	v_pk_add_f32 v[72:73], v[66:67], 0 op_sel_hi:[1,0]
	v_pk_add_f32 v[66:67], v[64:65], 0 op_sel_hi:[1,0]
	v_cvt_pk_bf16_f32 v64, v68, v69
	v_cvt_pk_bf16_f32 v65, v70, v71
	v_cvt_pk_bf16_f32 v66, v66, v67
	v_cvt_pk_bf16_f32 v67, v72, v73
	s_and_b64 vcc, exec, s[4:5]
	global_store_dwordx4 v[80:81], v[64:67], off offset:256 nt
	s_cbranch_vccnz .LBB0_170
	v_lshlrev_b32_e32 v69, 16, v65
	v_lshlrev_b32_e32 v68, 16, v64
	v_and_b32_e32 v65, 0xffff0000, v65
	v_and_b32_e32 v64, 0xffff0000, v64
	v_pk_mul_f32 v[64:65], v[64:65], v[64:65]
	v_and_b32_e32 v71, 0xffff0000, v66
	v_and_b32_e32 v70, 0xffff0000, v67
	v_pk_fma_f32 v[64:65], v[68:69], v[68:69], v[64:65]
	v_lshlrev_b32_e32 v69, 16, v66
	v_lshlrev_b32_e32 v68, 16, v67
	v_pk_mul_f32 v[66:67], v[70:71], v[70:71]
	v_add_f32_e32 v64, v64, v65
	v_pk_fma_f32 v[66:67], v[68:69], v[68:69], v[66:67]
	v_xor_b32_e32 v65, 16, v164
	v_add_f32_e32 v64, v64, v67
	v_add_f32_e32 v64, v66, v64
	v_and_b32_e32 v66, 64, v164
	v_add_u32_e32 v66, 64, v66
	v_cmp_lt_i32_e32 vcc, v65, v66
	s_nop 1
	v_cndmask_b32_e32 v65, v164, v65, vcc
	v_lshlrev_b32_e32 v65, 2, v65
	ds_bpermute_b32 v65, v65, v64
	s_waitcnt lgkmcnt(0)
	v_add_f32_e32 v64, v64, v65
	v_xor_b32_e32 v65, 32, v164
	v_cmp_lt_i32_e32 vcc, v65, v66
	s_nop 1
	v_cndmask_b32_e32 v65, v164, v65, vcc
	v_lshlrev_b32_e32 v65, 2, v65
	ds_bpermute_b32 v65, v65, v64
	s_waitcnt lgkmcnt(0)
	v_add_f32_e32 v64, v64, v65
	v_max_f32_e32 v65, v121, v121
	v_max_f32_e32 v121, v65, v64
.LBB0_170:
	s_nop 0
	v_add_u32_e32 v66, 0x80, v165
	v_mov_b64_e32 v[64:65], s[78:79]
	v_mad_i64_i32 v[64:65], s[50:51], v66, s76, v[64:65]
	v_pk_add_f32 v[62:63], v[62:63], 0 op_sel_hi:[1,0]
	v_pk_add_f32 v[60:61], v[60:61], 0 op_sel_hi:[1,0]
	v_pk_add_f32 v[66:67], v[58:59], 0 op_sel_hi:[1,0]
	v_pk_add_f32 v[58:59], v[56:57], 0 op_sel_hi:[1,0]
	v_lshl_add_u64 v[64:65], v[146:147], 1, v[64:65]
	v_cvt_pk_bf16_f32 v56, v60, v61
	v_cvt_pk_bf16_f32 v57, v62, v63
	v_cvt_pk_bf16_f32 v58, v58, v59
	v_cvt_pk_bf16_f32 v59, v66, v67
	s_and_b64 vcc, exec, s[4:5]
	global_store_dwordx4 v[64:65], v[56:59], off nt
	s_cbranch_vccnz .LBB0_172
	v_lshlrev_b32_e32 v61, 16, v57
	v_lshlrev_b32_e32 v60, 16, v56
	v_and_b32_e32 v57, 0xffff0000, v57
	v_and_b32_e32 v56, 0xffff0000, v56
	v_pk_mul_f32 v[56:57], v[56:57], v[56:57]
	v_and_b32_e32 v63, 0xffff0000, v58
	v_and_b32_e32 v62, 0xffff0000, v59
	v_pk_fma_f32 v[56:57], v[60:61], v[60:61], v[56:57]
	v_lshlrev_b32_e32 v61, 16, v58
	v_lshlrev_b32_e32 v60, 16, v59
	v_pk_mul_f32 v[58:59], v[62:63], v[62:63]
	v_add_f32_e32 v56, v56, v57
	v_pk_fma_f32 v[58:59], v[60:61], v[60:61], v[58:59]
	v_xor_b32_e32 v57, 16, v164
	v_add_f32_e32 v56, v56, v59
	v_add_f32_e32 v56, v58, v56
	v_and_b32_e32 v58, 64, v164
	v_add_u32_e32 v58, 64, v58
	v_cmp_lt_i32_e32 vcc, v57, v58
	s_nop 1
	v_cndmask_b32_e32 v57, v164, v57, vcc
	v_lshlrev_b32_e32 v57, 2, v57
	ds_bpermute_b32 v57, v57, v56
	s_waitcnt lgkmcnt(0)
	v_add_f32_e32 v56, v56, v57
	v_xor_b32_e32 v57, 32, v164
	v_cmp_lt_i32_e32 vcc, v57, v58
	s_nop 1
	v_cndmask_b32_e32 v57, v164, v57, vcc
	v_lshlrev_b32_e32 v57, 2, v57
	ds_bpermute_b32 v57, v57, v56
	s_waitcnt lgkmcnt(0)
	v_add_f32_e32 v56, v56, v57
	v_max_f32_e32 v57, v120, v120
	v_max_f32_e32 v120, v57, v56
.LBB0_172:
	v_pk_add_f32 v[54:55], v[54:55], 0 op_sel_hi:[1,0]
	v_pk_add_f32 v[52:53], v[52:53], 0 op_sel_hi:[1,0]
	v_pk_add_f32 v[56:57], v[50:51], 0 op_sel_hi:[1,0]
	v_pk_add_f32 v[50:51], v[48:49], 0 op_sel_hi:[1,0]
	v_cvt_pk_bf16_f32 v48, v52, v53
	v_cvt_pk_bf16_f32 v49, v54, v55
	v_cvt_pk_bf16_f32 v50, v50, v51
	v_cvt_pk_bf16_f32 v51, v56, v57
	s_and_b64 vcc, exec, s[4:5]
	global_store_dwordx4 v[64:65], v[48:51], off offset:256 nt
	s_cbranch_vccnz .LBB0_174
	v_lshlrev_b32_e32 v53, 16, v49
	v_lshlrev_b32_e32 v52, 16, v48
	v_and_b32_e32 v49, 0xffff0000, v49
	v_and_b32_e32 v48, 0xffff0000, v48
	v_pk_mul_f32 v[48:49], v[48:49], v[48:49]
	v_and_b32_e32 v55, 0xffff0000, v50
	v_and_b32_e32 v54, 0xffff0000, v51
	v_pk_fma_f32 v[48:49], v[52:53], v[52:53], v[48:49]
	v_lshlrev_b32_e32 v53, 16, v50
	v_lshlrev_b32_e32 v52, 16, v51
	v_pk_mul_f32 v[50:51], v[54:55], v[54:55]
	v_add_f32_e32 v48, v48, v49
	v_pk_fma_f32 v[50:51], v[52:53], v[52:53], v[50:51]
	v_xor_b32_e32 v49, 16, v164
	v_add_f32_e32 v48, v48, v51
	v_add_f32_e32 v48, v50, v48
	v_and_b32_e32 v50, 64, v164
	v_add_u32_e32 v50, 64, v50
	v_cmp_lt_i32_e32 vcc, v49, v50
	s_nop 1
	v_cndmask_b32_e32 v49, v164, v49, vcc
	v_lshlrev_b32_e32 v49, 2, v49
	ds_bpermute_b32 v49, v49, v48
	s_waitcnt lgkmcnt(0)
	v_add_f32_e32 v48, v48, v49
	v_xor_b32_e32 v49, 32, v164
	v_cmp_lt_i32_e32 vcc, v49, v50
	s_nop 1
	v_cndmask_b32_e32 v49, v164, v49, vcc
	v_lshlrev_b32_e32 v49, 2, v49
	ds_bpermute_b32 v49, v49, v48
	s_waitcnt lgkmcnt(0)
	v_add_f32_e32 v48, v48, v49
	v_max_f32_e32 v49, v121, v121
	v_max_f32_e32 v121, v49, v48
; __device__ __forceinline__ unsigned cvt_pk_bf16(float lo, float hi) { f32x2c_t v = {lo, hi}; bf16x2c_t b = __builtin_convertvector(v, bf16x2c_t); return __builtin_bit_cast(unsigned, b); }
; __device__ __forceinline__ float bf_lo(unsigned w) { return __uint_as_float(w << 16); }
; __device__ __forceinline__ float bf_hi(unsigned w) { return __uint_as_float(w & 0xffff0000u); }
;     __device__ __forceinline__ void operator()(const f32x4 (&acc)[2][2][4][2], const Unit& u, int wr, int wc, int fr, int fq) const {
;     ...
;             for (int m = 0; m < 4; ++m) { bf16_t* rowp = O + (size_t)(row0 + ai * HALF + m * 16) * ldc + col0;
; #pragma unroll
;                 for (int bj = 0; bj < 2; ++bj) { const f32x4 v0 = acc[ai][bj][m][0] + 0.f, v1 = acc[ai][bj][m][1] + 0.f;
;                     u32x4 w; w.x = cvt_pk_bf16(v0[0], v0[1]); w.y = cvt_pk_bf16(v0[2], v0[3]); w.z = cvt_pk_bf16(v1[0], v1[1]); w.w = cvt_pk_bf16(v1[2], v1[3]);
;                     *(u32x4*)(rowp + bj * HALF) = w;
;                     if (isk) { float q = (bf_lo(w.x) * bf_lo(w.x) + bf_hi(w.x) * bf_hi(w.x)) + (bf_lo(w.y) * bf_lo(w.y) + bf_hi(w.y) * bf_hi(w.y))
;                                        + (bf_lo(w.z) * bf_lo(w.z) + bf_hi(w.z) * bf_hi(w.z)) + (bf_lo(w.w) * bf_lo(w.w) + bf_hi(w.w) * bf_hi(w.w));
;                         q += __shfl_xor(q, 16); q += __shfl_xor(q, 32); kmx[bj] = fmaxf(kmx[bj], q); } } }
.LBB0_174:
	s_nop 0
	v_add_u32_e32 v50, 0x90, v165
	v_mov_b64_e32 v[48:49], s[78:79]
	v_mad_i64_i32 v[48:49], s[50:51], v50, s76, v[48:49]
	v_pk_add_f32 v[46:47], v[46:47], 0 op_sel_hi:[1,0]
	v_pk_add_f32 v[44:45], v[44:45], 0 op_sel_hi:[1,0]
	v_pk_add_f32 v[50:51], v[42:43], 0 op_sel_hi:[1,0]
	v_pk_add_f32 v[42:43], v[40:41], 0 op_sel_hi:[1,0]
	v_lshl_add_u64 v[48:49], v[146:147], 1, v[48:49]
	v_cvt_pk_bf16_f32 v40, v44, v45
	v_cvt_pk_bf16_f32 v41, v46, v47
	v_cvt_pk_bf16_f32 v42, v42, v43
	v_cvt_pk_bf16_f32 v43, v50, v51
	s_and_b64 vcc, exec, s[4:5]
	global_store_dwordx4 v[48:49], v[40:43], off nt
	s_cbranch_vccnz .LBB0_176
	v_lshlrev_b32_e32 v45, 16, v41
	v_lshlrev_b32_e32 v44, 16, v40
	v_and_b32_e32 v41, 0xffff0000, v41
	v_and_b32_e32 v40, 0xffff0000, v40
	v_pk_mul_f32 v[40:41], v[40:41], v[40:41]
	v_and_b32_e32 v47, 0xffff0000, v42
	v_and_b32_e32 v46, 0xffff0000, v43
	v_pk_fma_f32 v[40:41], v[44:45], v[44:45], v[40:41]
	v_lshlrev_b32_e32 v45, 16, v42
	v_lshlrev_b32_e32 v44, 16, v43
	v_pk_mul_f32 v[42:43], v[46:47], v[46:47]
	v_add_f32_e32 v40, v40, v41
	v_pk_fma_f32 v[42:43], v[44:45], v[44:45], v[42:43]
	v_xor_b32_e32 v41, 16, v164
	v_add_f32_e32 v40, v40, v43
	v_add_f32_e32 v40, v42, v40
	v_and_b32_e32 v42, 64, v164
	v_add_u32_e32 v42, 64, v42
	v_cmp_lt_i32_e32 vcc, v41, v42
	s_nop 1
	v_cndmask_b32_e32 v41, v164, v41, vcc
	v_lshlrev_b32_e32 v41, 2, v41
	ds_bpermute_b32 v41, v41, v40
	s_waitcnt lgkmcnt(0)
	v_add_f32_e32 v40, v40, v41
	v_xor_b32_e32 v41, 32, v164
	v_cmp_lt_i32_e32 vcc, v41, v42
	s_nop 1
	v_cndmask_b32_e32 v41, v164, v41, vcc
	v_lshlrev_b32_e32 v41, 2, v41
	ds_bpermute_b32 v41, v41, v40
	s_waitcnt lgkmcnt(0)
	v_add_f32_e32 v40, v40, v41
	v_max_f32_e32 v41, v120, v120
	v_max_f32_e32 v120, v41, v40
.LBB0_176:
	v_pk_add_f32 v[38:39], v[38:39], 0 op_sel_hi:[1,0]
	v_pk_add_f32 v[36:37], v[36:37], 0 op_sel_hi:[1,0]
	v_pk_add_f32 v[40:41], v[34:35], 0 op_sel_hi:[1,0]
	v_pk_add_f32 v[34:35], v[32:33], 0 op_sel_hi:[1,0]
	v_cvt_pk_bf16_f32 v32, v36, v37
	v_cvt_pk_bf16_f32 v33, v38, v39
	v_cvt_pk_bf16_f32 v34, v34, v35
	v_cvt_pk_bf16_f32 v35, v40, v41
	s_and_b64 vcc, exec, s[4:5]
	global_store_dwordx4 v[48:49], v[32:35], off offset:256 nt
	s_cbranch_vccnz .LBB0_178
	v_lshlrev_b32_e32 v37, 16, v33
	v_lshlrev_b32_e32 v36, 16, v32
	v_and_b32_e32 v33, 0xffff0000, v33
	v_and_b32_e32 v32, 0xffff0000, v32
	v_pk_mul_f32 v[32:33], v[32:33], v[32:33]
	v_and_b32_e32 v39, 0xffff0000, v34
	v_and_b32_e32 v38, 0xffff0000, v35
	v_pk_fma_f32 v[32:33], v[36:37], v[36:37], v[32:33]
	v_lshlrev_b32_e32 v37, 16, v34
	v_lshlrev_b32_e32 v36, 16, v35
	v_pk_mul_f32 v[34:35], v[38:39], v[38:39]
	v_add_f32_e32 v32, v32, v33
	v_pk_fma_f32 v[34:35], v[36:37], v[36:37], v[34:35]
	v_xor_b32_e32 v33, 16, v164
	v_add_f32_e32 v32, v32, v35
	v_add_f32_e32 v32, v34, v32
	v_and_b32_e32 v34, 64, v164
	v_add_u32_e32 v34, 64, v34
	v_cmp_lt_i32_e32 vcc, v33, v34
	s_nop 1
	v_cndmask_b32_e32 v33, v164, v33, vcc
	v_lshlrev_b32_e32 v33, 2, v33
	ds_bpermute_b32 v33, v33, v32
	s_waitcnt lgkmcnt(0)
	v_add_f32_e32 v32, v32, v33
	v_xor_b32_e32 v33, 32, v164
	v_cmp_lt_i32_e32 vcc, v33, v34
	s_nop 1
	v_cndmask_b32_e32 v33, v164, v33, vcc
	v_lshlrev_b32_e32 v33, 2, v33
	ds_bpermute_b32 v33, v33, v32
	s_waitcnt lgkmcnt(0)
	v_add_f32_e32 v32, v32, v33
	v_max_f32_e32 v33, v121, v121
	v_max_f32_e32 v121, v33, v32
.LBB0_178:
	s_nop 0
	v_add_u32_e32 v34, 0xa0, v165
	v_mov_b64_e32 v[32:33], s[78:79]
	v_mad_i64_i32 v[32:33], s[50:51], v34, s76, v[32:33]
	v_pk_add_f32 v[30:31], v[30:31], 0 op_sel_hi:[1,0]
	v_pk_add_f32 v[28:29], v[28:29], 0 op_sel_hi:[1,0]
	v_pk_add_f32 v[34:35], v[26:27], 0 op_sel_hi:[1,0]
	v_pk_add_f32 v[26:27], v[24:25], 0 op_sel_hi:[1,0]
	v_lshl_add_u64 v[32:33], v[146:147], 1, v[32:33]
	v_cvt_pk_bf16_f32 v24, v28, v29
	v_cvt_pk_bf16_f32 v25, v30, v31
	v_cvt_pk_bf16_f32 v26, v26, v27
	v_cvt_pk_bf16_f32 v27, v34, v35
	s_and_b64 vcc, exec, s[4:5]
	global_store_dwordx4 v[32:33], v[24:27], off nt
	s_cbranch_vccnz .LBB0_180
	v_lshlrev_b32_e32 v29, 16, v25
	v_lshlrev_b32_e32 v28, 16, v24
	v_and_b32_e32 v25, 0xffff0000, v25
	v_and_b32_e32 v24, 0xffff0000, v24
	v_pk_mul_f32 v[24:25], v[24:25], v[24:25]
	v_and_b32_e32 v31, 0xffff0000, v26
	v_and_b32_e32 v30, 0xffff0000, v27
	v_pk_fma_f32 v[24:25], v[28:29], v[28:29], v[24:25]
	v_lshlrev_b32_e32 v29, 16, v26
	v_lshlrev_b32_e32 v28, 16, v27
	v_pk_mul_f32 v[26:27], v[30:31], v[30:31]
	v_add_f32_e32 v24, v24, v25
	v_pk_fma_f32 v[26:27], v[28:29], v[28:29], v[26:27]
	v_xor_b32_e32 v25, 16, v164
	v_add_f32_e32 v24, v24, v27
	v_add_f32_e32 v24, v26, v24
	v_and_b32_e32 v26, 64, v164
	v_add_u32_e32 v26, 64, v26
	v_cmp_lt_i32_e32 vcc, v25, v26
	s_nop 1
	v_cndmask_b32_e32 v25, v164, v25, vcc
	v_lshlrev_b32_e32 v25, 2, v25
	ds_bpermute_b32 v25, v25, v24
	s_waitcnt lgkmcnt(0)
	v_add_f32_e32 v24, v24, v25
	v_xor_b32_e32 v25, 32, v164
	v_cmp_lt_i32_e32 vcc, v25, v26
	s_nop 1
	v_cndmask_b32_e32 v25, v164, v25, vcc
	v_lshlrev_b32_e32 v25, 2, v25
	ds_bpermute_b32 v25, v25, v24
	s_waitcnt lgkmcnt(0)
	v_add_f32_e32 v24, v24, v25
	v_max_f32_e32 v25, v120, v120
	v_max_f32_e32 v120, v25, v24
; __device__ __forceinline__ unsigned cvt_pk_bf16(float lo, float hi) { f32x2c_t v = {lo, hi}; bf16x2c_t b = __builtin_convertvector(v, bf16x2c_t); return __builtin_bit_cast(unsigned, b); }
; __device__ __forceinline__ float bf_lo(unsigned w) { return __uint_as_float(w << 16); }
; __device__ __forceinline__ float bf_hi(unsigned w) { return __uint_as_float(w & 0xffff0000u); }
;     __device__ __forceinline__ void operator()(const f32x4 (&acc)[2][2][4][2], const Unit& u, int wr, int wc, int fr, int fq) const {
;     ...
;             for (int m = 0; m < 4; ++m) { bf16_t* rowp = O + (size_t)(row0 + ai * HALF + m * 16) * ldc + col0;
; #pragma unroll
;                 for (int bj = 0; bj < 2; ++bj) { const f32x4 v0 = acc[ai][bj][m][0] + 0.f, v1 = acc[ai][bj][m][1] + 0.f;
;                     u32x4 w; w.x = cvt_pk_bf16(v0[0], v0[1]); w.y = cvt_pk_bf16(v0[2], v0[3]); w.z = cvt_pk_bf16(v1[0], v1[1]); w.w = cvt_pk_bf16(v1[2], v1[3]);
;                     *(u32x4*)(rowp + bj * HALF) = w;
;                     if (isk) { float q = (bf_lo(w.x) * bf_lo(w.x) + bf_hi(w.x) * bf_hi(w.x)) + (bf_lo(w.y) * bf_lo(w.y) + bf_hi(w.y) * bf_hi(w.y))
;                                        + (bf_lo(w.z) * bf_lo(w.z) + bf_hi(w.z) * bf_hi(w.z)) + (bf_lo(w.w) * bf_lo(w.w) + bf_hi(w.w) * bf_hi(w.w));
;                         q += __shfl_xor(q, 16); q += __shfl_xor(q, 32); kmx[bj] = fmaxf(kmx[bj], q); } } }
;         if (isk) {
; #pragma unroll
;             for (int bj = 0; bj < 2; ++bj) { float q = kmx[bj];
; #pragma unroll
;                 for (int o = 1; o < 16; o <<= 1) q = fmaxf(q, __shfl_xor(q, o));
;                 if (fr == 0 && fq == 0) { const int b = u.pm >> 4, map = (u.pn - 4) * 4 + bj * 2 + (wc >> 1), half = wc & 1;
;                     atomicMax(khalf + (b * 16 + map) * 2 + half, __float_as_uint(q * 1.02f)); } }
.LBB0_180:
	v_pk_add_f32 v[22:23], v[22:23], 0 op_sel_hi:[1,0]
	v_pk_add_f32 v[20:21], v[20:21], 0 op_sel_hi:[1,0]
	v_pk_add_f32 v[24:25], v[18:19], 0 op_sel_hi:[1,0]
	v_pk_add_f32 v[18:19], v[16:17], 0 op_sel_hi:[1,0]
	v_cvt_pk_bf16_f32 v16, v20, v21
	v_cvt_pk_bf16_f32 v17, v22, v23
	v_cvt_pk_bf16_f32 v18, v18, v19
	v_cvt_pk_bf16_f32 v19, v24, v25
	s_and_b64 vcc, exec, s[4:5]
	global_store_dwordx4 v[32:33], v[16:19], off offset:256 nt
	s_cbranch_vccnz .LBB0_182
	v_lshlrev_b32_e32 v21, 16, v17
	v_lshlrev_b32_e32 v20, 16, v16
	v_and_b32_e32 v17, 0xffff0000, v17
	v_and_b32_e32 v16, 0xffff0000, v16
	v_pk_mul_f32 v[16:17], v[16:17], v[16:17]
	v_and_b32_e32 v23, 0xffff0000, v18
	v_and_b32_e32 v22, 0xffff0000, v19
	v_pk_fma_f32 v[16:17], v[20:21], v[20:21], v[16:17]
	v_lshlrev_b32_e32 v21, 16, v18
	v_lshlrev_b32_e32 v20, 16, v19
	v_pk_mul_f32 v[18:19], v[22:23], v[22:23]
	v_add_f32_e32 v16, v16, v17
	v_pk_fma_f32 v[18:19], v[20:21], v[20:21], v[18:19]
	v_xor_b32_e32 v17, 16, v164
	v_add_f32_e32 v16, v16, v19
	v_add_f32_e32 v16, v18, v16
	v_and_b32_e32 v18, 64, v164
	v_add_u32_e32 v18, 64, v18
	v_cmp_lt_i32_e32 vcc, v17, v18
	s_nop 1
	v_cndmask_b32_e32 v17, v164, v17, vcc
	v_lshlrev_b32_e32 v17, 2, v17
	ds_bpermute_b32 v17, v17, v16
	s_waitcnt lgkmcnt(0)
	v_add_f32_e32 v16, v16, v17
	v_xor_b32_e32 v17, 32, v164
	v_cmp_lt_i32_e32 vcc, v17, v18
	s_nop 1
	v_cndmask_b32_e32 v17, v164, v17, vcc
	v_lshlrev_b32_e32 v17, 2, v17
	ds_bpermute_b32 v17, v17, v16
	s_waitcnt lgkmcnt(0)
	v_add_f32_e32 v16, v16, v17
	v_max_f32_e32 v17, v121, v121
	v_max_f32_e32 v121, v17, v16
.LBB0_182:
	s_nop 0
	v_add_u32_e32 v18, 0xb0, v165
	v_mov_b64_e32 v[16:17], s[78:79]
	v_mad_i64_i32 v[16:17], s[50:51], v18, s76, v[16:17]
	v_pk_add_f32 v[14:15], v[14:15], 0 op_sel_hi:[1,0]
	v_pk_add_f32 v[12:13], v[12:13], 0 op_sel_hi:[1,0]
	v_pk_add_f32 v[18:19], v[10:11], 0 op_sel_hi:[1,0]
	v_pk_add_f32 v[10:11], v[8:9], 0 op_sel_hi:[1,0]
	v_lshl_add_u64 v[16:17], v[146:147], 1, v[16:17]
	v_cvt_pk_bf16_f32 v8, v12, v13
	v_cvt_pk_bf16_f32 v9, v14, v15
	v_cvt_pk_bf16_f32 v10, v10, v11
	v_cvt_pk_bf16_f32 v11, v18, v19
	s_and_b64 vcc, exec, s[4:5]
	global_store_dwordx4 v[16:17], v[8:11], off nt
	s_cbranch_vccnz .LBB0_184
	v_lshlrev_b32_e32 v13, 16, v9
	v_lshlrev_b32_e32 v12, 16, v8
	v_and_b32_e32 v9, 0xffff0000, v9
	v_and_b32_e32 v8, 0xffff0000, v8
	v_pk_mul_f32 v[8:9], v[8:9], v[8:9]
	v_and_b32_e32 v15, 0xffff0000, v10
	v_and_b32_e32 v14, 0xffff0000, v11
	v_pk_fma_f32 v[8:9], v[12:13], v[12:13], v[8:9]
	v_lshlrev_b32_e32 v13, 16, v10
	v_lshlrev_b32_e32 v12, 16, v11
	v_pk_mul_f32 v[10:11], v[14:15], v[14:15]
	v_add_f32_e32 v8, v8, v9
	v_pk_fma_f32 v[10:11], v[12:13], v[12:13], v[10:11]
	v_xor_b32_e32 v9, 16, v164
	v_add_f32_e32 v8, v8, v11
	v_add_f32_e32 v8, v10, v8
	v_and_b32_e32 v10, 64, v164
	v_add_u32_e32 v10, 64, v10
	v_cmp_lt_i32_e32 vcc, v9, v10
	s_nop 1
	v_cndmask_b32_e32 v9, v164, v9, vcc
	v_lshlrev_b32_e32 v9, 2, v9
	ds_bpermute_b32 v9, v9, v8
	s_waitcnt lgkmcnt(0)
	v_add_f32_e32 v8, v8, v9
	v_xor_b32_e32 v9, 32, v164
	v_cmp_lt_i32_e32 vcc, v9, v10
	s_nop 1
	v_cndmask_b32_e32 v9, v164, v9, vcc
	v_lshlrev_b32_e32 v9, 2, v9
	ds_bpermute_b32 v9, v9, v8
	s_waitcnt lgkmcnt(0)
	v_add_f32_e32 v8, v8, v9
	v_max_f32_e32 v9, v120, v120
	v_max_f32_e32 v120, v9, v8
.LBB0_184:
	v_pk_add_f32 v[6:7], v[6:7], 0 op_sel_hi:[1,0]
	v_pk_add_f32 v[4:5], v[4:5], 0 op_sel_hi:[1,0]
	v_pk_add_f32 v[8:9], v[2:3], 0 op_sel_hi:[1,0]
	v_pk_add_f32 v[2:3], v[0:1], 0 op_sel_hi:[1,0]
	v_cvt_pk_bf16_f32 v0, v4, v5
	v_cvt_pk_bf16_f32 v1, v6, v7
	v_cvt_pk_bf16_f32 v2, v2, v3
	v_cvt_pk_bf16_f32 v3, v8, v9
	s_and_b64 vcc, exec, s[4:5]
	global_store_dwordx4 v[16:17], v[0:3], off offset:256 nt
	s_cbranch_vccnz .LBB0_196
	v_lshlrev_b32_e32 v4, 16, v0
	v_and_b32_e32 v0, 0xffff0000, v0
	v_mul_f32_e32 v0, v0, v0
	v_fmac_f32_e32 v0, v4, v4
	v_lshlrev_b32_e32 v4, 16, v1
	v_and_b32_e32 v1, 0xffff0000, v1
	v_mul_f32_e32 v1, v1, v1
	v_fmac_f32_e32 v1, v4, v4
	v_add_f32_e32 v0, v0, v1
	v_lshlrev_b32_e32 v1, 16, v2
	v_and_b32_e32 v2, 0xffff0000, v2
	v_mul_f32_e32 v2, v2, v2
	v_fmac_f32_e32 v2, v1, v1
	v_add_f32_e32 v0, v0, v2
	v_and_b32_e32 v2, 0xffff0000, v3
	v_lshlrev_b32_e32 v1, 16, v3
	v_mul_f32_e32 v2, v2, v2
	v_fmac_f32_e32 v2, v1, v1
	v_add_f32_e32 v2, v2, v0
	v_and_b32_e32 v0, 64, v164
	v_add_u32_e32 v4, 64, v0
	v_xor_b32_e32 v0, 1, v164
	v_cmp_lt_i32_e32 vcc, v0, v4
	v_xor_b32_e32 v1, 16, v164
	s_nop 0
	v_cndmask_b32_e32 v0, v164, v0, vcc
	v_lshlrev_b32_e32 v0, 2, v0
	ds_bpermute_b32 v3, v0, v120
	v_cmp_lt_i32_e32 vcc, v1, v4
	s_nop 1
	v_cndmask_b32_e32 v1, v164, v1, vcc
	v_lshlrev_b32_e32 v1, 2, v1
	ds_bpermute_b32 v5, v1, v2
	s_waitcnt lgkmcnt(0)
	v_max_f32_e32 v1, v3, v3
	v_max_f32_e32 v3, v120, v120
	v_max_f32_e32 v6, v3, v1
	v_xor_b32_e32 v1, 2, v164
	v_cmp_lt_i32_e32 vcc, v1, v4
	v_add_f32_e32 v3, v2, v5
	v_xor_b32_e32 v5, 32, v164
	v_cndmask_b32_e32 v1, v164, v1, vcc
	v_lshlrev_b32_e32 v1, 2, v1
	ds_bpermute_b32 v7, v1, v6
	s_waitcnt lgkmcnt(0)
	v_max_f32_e32 v2, v7, v7
	v_max_f32_e32 v6, v6, v2
	v_xor_b32_e32 v2, 4, v164
	v_cmp_lt_i32_e32 vcc, v2, v4
	s_nop 1
	v_cndmask_b32_e32 v2, v164, v2, vcc
	v_lshlrev_b32_e32 v2, 2, v2
	ds_bpermute_b32 v7, v2, v6
	v_cmp_lt_i32_e32 vcc, v5, v4
	s_waitcnt lgkmcnt(0)
	v_max_f32_e32 v7, v7, v7
	v_max_f32_e32 v6, v6, v7
	v_xor_b32_e32 v7, 8, v164
	v_cndmask_b32_e32 v5, v164, v5, vcc
	v_cmp_lt_i32_e32 vcc, v7, v4
	v_lshlrev_b32_e32 v5, 2, v5
	ds_bpermute_b32 v5, v5, v3
	v_cndmask_b32_e32 v4, v164, v7, vcc
	v_lshlrev_b32_e32 v4, 2, v4
	ds_bpermute_b32 v7, v4, v6
	s_and_saveexec_b64 s[4:5], s[0:1]
	s_cbranch_execz .LBB0_190
	s_waitcnt lgkmcnt(0)
	v_max_f32_e32 v7, v7, v7
	v_max_f32_e32 v6, v6, v6
	v_max_f32_e32 v6, v6, v7
	s_mov_b64 s[50:51], exec
	v_mul_f32_e32 v6, 0x3f828f5c, v6
	s_mov_b32 s43, 0

; __device__ __forceinline__ void transpose_item(const float* W, int K, int N, int c0, int ncols, bf16_t* WT, int row_off, float scale, LAS float* scr, int item, int lane) {
;     ...
; #pragma unroll 8
;     for (int i = 0; i < 32; ++i) { const int kk = 2 * i + (lane >> 5); scr[kk * 33 + (lane & 31)] = W[(size_t)(k0 + kk) * N + c0 + n0 + (lane & 31)] * scale; }
;     asm volatile("s_waitcnt lgkmcnt(0)" ::: "memory");
.LBB0_230:
	s_lshl_b32 s34, s0, 1
	s_lshl_b32 s35, s5, 1
	v_or_b32_e32 v36, s35, v2
	s_add_i32 s36, s34, 4
	s_add_i32 s37, s35, 4
	s_add_i32 s38, s34, 8
	s_add_i32 s39, s35, 8
	s_add_i32 s40, s34, 12
	s_add_i32 s41, s35, 12
	s_add_i32 s42, s34, 16
	s_add_i32 s43, s35, 16
	s_add_i32 s44, s34, 20
	s_add_i32 s45, s35, 20
	s_add_i32 s46, s34, 24
	s_add_i32 s47, s35, 24
	s_add_i32 s48, s34, 28
	s_add_i32 s49, s35, 28
	v_or_b32_e32 v34, s34, v5
	v_ashrrev_i32_e32 v37, 31, v36
	v_or_b32_e32 v38, s36, v5
	v_or_b32_e32 v40, s37, v2
	v_or_b32_e32 v42, s38, v5
	v_or_b32_e32 v44, s39, v2
	v_or_b32_e32 v46, s40, v5
	v_or_b32_e32 v48, s41, v2
	v_or_b32_e32 v50, s42, v5
	v_or_b32_e32 v52, s43, v2
	v_or_b32_e32 v54, s44, v5
	v_or_b32_e32 v56, s45, v2
	v_or_b32_e32 v58, s46, v5
	v_or_b32_e32 v60, s47, v2
	v_or_b32_e32 v62, s48, v5
	v_or_b32_e32 v64, s49, v2
	v_ashrrev_i32_e32 v35, 31, v34
	v_lshlrev_b64 v[36:37], 12, v[36:37]
	v_ashrrev_i32_e32 v41, 31, v40
	v_ashrrev_i32_e32 v39, 31, v38
	v_ashrrev_i32_e32 v45, 31, v44
	v_ashrrev_i32_e32 v43, 31, v42
	v_ashrrev_i32_e32 v49, 31, v48
	v_ashrrev_i32_e32 v47, 31, v46
	v_ashrrev_i32_e32 v53, 31, v52
	v_ashrrev_i32_e32 v51, 31, v50
	v_ashrrev_i32_e32 v57, 31, v56
	v_ashrrev_i32_e32 v55, 31, v54
	v_ashrrev_i32_e32 v61, 31, v60
	v_ashrrev_i32_e32 v59, 31, v58
	v_ashrrev_i32_e32 v65, 31, v64
	v_ashrrev_i32_e32 v63, 31, v62
	v_lshlrev_b64 v[34:35], 12, v[34:35]
	v_lshl_add_u64 v[36:37], v[26:27], 0, v[36:37]
	v_lshlrev_b64 v[38:39], 12, v[38:39]
	v_lshlrev_b64 v[40:41], 12, v[40:41]
	v_lshlrev_b64 v[42:43], 12, v[42:43]
	v_lshlrev_b64 v[44:45], 12, v[44:45]
	v_lshlrev_b64 v[46:47], 12, v[46:47]
	v_lshlrev_b64 v[48:49], 12, v[48:49]
	v_lshlrev_b64 v[50:51], 12, v[50:51]
	v_lshlrev_b64 v[52:53], 12, v[52:53]
	v_lshlrev_b64 v[54:55], 12, v[54:55]
	v_lshlrev_b64 v[56:57], 12, v[56:57]
	v_lshlrev_b64 v[58:59], 12, v[58:59]
	v_lshlrev_b64 v[60:61], 12, v[60:61]
	v_lshlrev_b64 v[62:63], 12, v[62:63]
	v_lshlrev_b64 v[64:65], 12, v[64:65]
	v_lshl_add_u64 v[34:35], v[26:27], 0, v[34:35]
	v_lshl_add_u64 v[40:41], v[26:27], 0, v[40:41]
	v_lshl_add_u64 v[38:39], v[26:27], 0, v[38:39]
	v_lshl_add_u64 v[44:45], v[26:27], 0, v[44:45]
	v_lshl_add_u64 v[42:43], v[26:27], 0, v[42:43]
	v_lshl_add_u64 v[48:49], v[26:27], 0, v[48:49]
	v_lshl_add_u64 v[46:47], v[26:27], 0, v[46:47]
	v_lshl_add_u64 v[52:53], v[26:27], 0, v[52:53]
	v_lshl_add_u64 v[50:51], v[26:27], 0, v[50:51]
	v_lshl_add_u64 v[56:57], v[26:27], 0, v[56:57]
	v_lshl_add_u64 v[54:55], v[26:27], 0, v[54:55]
	v_lshl_add_u64 v[60:61], v[26:27], 0, v[60:61]
	v_lshl_add_u64 v[58:59], v[26:27], 0, v[58:59]
	v_lshl_add_u64 v[64:65], v[26:27], 0, v[64:65]
	v_lshl_add_u64 v[62:63], v[26:27], 0, v[62:63]
	global_load_dword v25, v[36:37], off nt
	global_load_dword v28, v[34:35], off nt
	global_load_dword v66, v[40:41], off nt
	global_load_dword v67, v[38:39], off nt
	global_load_dword v68, v[44:45], off nt
	global_load_dword v69, v[42:43], off nt
	global_load_dword v70, v[48:49], off nt
	global_load_dword v71, v[46:47], off nt
	global_load_dword v72, v[52:53], off nt
	global_load_dword v73, v[50:51], off nt
	global_load_dword v74, v[56:57], off nt
	global_load_dword v75, v[54:55], off nt
	global_load_dword v76, v[60:61], off nt
	global_load_dword v77, v[58:59], off nt
	global_load_dword v78, v[64:65], off nt
	global_load_dword v79, v[62:63], off nt
	v_or_b32_e32 v36, s34, v1
	v_or_b32_e32 v34, s35, v0
	s_add_i32 s5, s5, 16
	s_add_i32 s0, s0, 16
	s_add_i32 s29, s29, -16
	v_mad_u64_u32 v[34:35], s[34:35], v34, s31, v[4:5]
	v_mad_u64_u32 v[36:37], s[34:35], v36, s31, v[4:5]
	v_or_b32_e32 v35, s36, v1
	v_or_b32_e32 v37, s37, v0
	v_or_b32_e32 v44, s38, v1
	v_or_b32_e32 v42, s39, v0
	v_or_b32_e32 v48, s40, v1
	v_or_b32_e32 v46, s41, v0
	v_or_b32_e32 v52, s42, v1
	v_or_b32_e32 v50, s43, v0
	v_or_b32_e32 v56, s44, v1
	v_or_b32_e32 v54, s45, v0
	v_or_b32_e32 v60, s46, v1
	v_or_b32_e32 v58, s47, v0
	v_or_b32_e32 v64, s48, v1
	v_or_b32_e32 v62, s49, v0
	s_cmp_lg_u32 s29, 0
	v_mad_u64_u32 v[38:39], s[34:35], v37, s31, v[4:5]
	v_mad_u64_u32 v[40:41], s[34:35], v35, s31, v[4:5]
	v_mad_u64_u32 v[42:43], s[34:35], v42, s31, v[4:5]
	v_mad_u64_u32 v[44:45], s[34:35], v44, s31, v[4:5]
	v_mad_u64_u32 v[46:47], s[34:35], v46, s31, v[4:5]
	v_mad_u64_u32 v[48:49], s[34:35], v48, s31, v[4:5]
	v_mad_u64_u32 v[50:51], s[34:35], v50, s31, v[4:5]
	v_mad_u64_u32 v[52:53], s[34:35], v52, s31, v[4:5]
	v_mad_u64_u32 v[54:55], s[34:35], v54, s31, v[4:5]
	v_mad_u64_u32 v[56:57], s[34:35], v56, s31, v[4:5]
	v_mad_u64_u32 v[58:59], s[34:35], v58, s31, v[4:5]
	v_mad_u64_u32 v[60:61], s[34:35], v60, s31, v[4:5]
	v_mad_u64_u32 v[62:63], s[34:35], v62, s31, v[4:5]
	v_mad_u64_u32 v[64:65], s[34:35], v64, s31, v[4:5]
	s_waitcnt vmcnt(0)
	ds_write_b32 v34, v25
	ds_write_b32 v36, v28
	ds_write_b32 v38, v66
	ds_write_b32 v40, v67
	ds_write_b32 v42, v68
	ds_write_b32 v44, v69
	ds_write_b32 v46, v70
	ds_write_b32 v48, v71
	ds_write_b32 v50, v72
	ds_write_b32 v52, v73
	ds_write_b32 v54, v74
	ds_write_b32 v56, v75
	ds_write_b32 v58, v76
	ds_write_b32 v60, v77
	ds_write_b32 v62, v78
	ds_write_b32 v64, v79
	s_cbranch_scc1 .LBB0_230
; #define LAS __attribute__((address_space(3)))
; __device__ __forceinline__ unsigned cvtpk(float lo, float hi) { return pg8::cvt_pk_bf16(lo, hi); }
; __device__ __forceinline__ void transpose_item(const float* W, int K, int N, int c0, int ncols, bf16_t* WT, int row_off, float scale, LAS float* scr, int item, int lane) {
;     ...
;     const int c = lane & 7;
; #pragma unroll
;     for (int j = 0; j < 4; ++j) { const int n = (lane >> 3) + 8 * j; const LAS float* s = scr + (8 * c) * 33 + n;
;         u32x4 o; o.x = cvtpk(s[0 * 33], s[1 * 33]); o.y = cvtpk(s[2 * 33], s[3 * 33]); o.z = cvtpk(s[4 * 33], s[5 * 33]); o.w = cvtpk(s[6 * 33], s[7 * 33]);
;         *(u32x4*)(WT + (size_t)(row_off + n0 + n) * K + k0 + 8 * c) = o; }
;     asm volatile("s_waitcnt lgkmcnt(0)" ::: "memory");
	s_waitcnt lgkmcnt(0)
	ds_read2_b32 v[26:27], v30 offset0:33 offset1:41
	ds_read2_b32 v[38:39], v30 offset1:8
	ds_read2_b32 v[40:41], v30 offset0:66 offset1:74
	ds_read2_b32 v[42:43], v30 offset0:99 offset1:107
	ds_read2_b32 v[44:45], v30 offset0:132 offset1:140
	ds_read2_b32 v[46:47], v30 offset0:165 offset1:173
	ds_read2_b32 v[48:49], v30 offset0:198 offset1:206
	ds_read2_b32 v[50:51], v30 offset0:231 offset1:239
	v_or_b32_e32 v54, s4, v29
	s_ashr_i32 s29, s28, 31
	v_ashrrev_i32_e32 v55, 31, v54
	v_lshl_add_u64 v[52:53], s[28:29], 1, v[14:15]
	v_lshlrev_b64 v[54:55], 11, v[54:55]
	s_waitcnt lgkmcnt(6)
	v_cvt_pk_bf16_f32 v34, v38, v26
	s_waitcnt lgkmcnt(4)
	v_cvt_pk_bf16_f32 v35, v40, v42
	s_waitcnt lgkmcnt(2)
	v_cvt_pk_bf16_f32 v36, v44, v46
	s_waitcnt lgkmcnt(0)
	v_cvt_pk_bf16_f32 v37, v48, v50
	v_lshl_add_u64 v[54:55], v[52:53], 0, v[54:55]
	v_or_b32_e32 v26, s4, v31
	global_store_dwordx4 v[54:55], v[34:37], off nt
	s_nop 1
	v_cvt_pk_bf16_f32 v34, v39, v27
	v_ashrrev_i32_e32 v27, 31, v26
	v_cvt_pk_bf16_f32 v35, v41, v43
	v_cvt_pk_bf16_f32 v36, v45, v47
	v_cvt_pk_bf16_f32 v37, v49, v51
	v_lshlrev_b64 v[26:27], 11, v[26:27]
	ds_read2_b32 v[38:39], v30 offset0:49 offset1:57
	ds_read2_b32 v[40:41], v30 offset0:16 offset1:24
	ds_read2_b32 v[42:43], v30 offset0:82 offset1:90
	ds_read2_b32 v[44:45], v30 offset0:115 offset1:123
	ds_read2_b32 v[46:47], v30 offset0:148 offset1:156
	ds_read2_b32 v[48:49], v30 offset0:181 offset1:189
	ds_read2_b32 v[50:51], v30 offset0:214 offset1:222
	ds_read2_b32 v[54:55], v30 offset0:247 offset1:255
	v_lshl_add_u64 v[26:27], v[52:53], 0, v[26:27]
	global_store_dwordx4 v[26:27], v[34:37], off nt
	v_or_b32_e32 v26, s4, v32
	v_ashrrev_i32_e32 v27, 31, v26
	v_lshlrev_b64 v[26:27], 11, v[26:27]
	s_waitcnt lgkmcnt(6)
	v_cvt_pk_bf16_f32 v34, v40, v38
	s_waitcnt lgkmcnt(4)
	v_cvt_pk_bf16_f32 v35, v42, v44
	s_waitcnt lgkmcnt(2)
	v_cvt_pk_bf16_f32 v36, v46, v48
	s_waitcnt lgkmcnt(0)
	v_cvt_pk_bf16_f32 v37, v50, v54
	v_lshl_add_u64 v[26:27], v[52:53], 0, v[26:27]
	global_store_dwordx4 v[26:27], v[34:37], off nt
	v_or_b32_e32 v26, s4, v33
	v_ashrrev_i32_e32 v27, 31, v26
	v_lshlrev_b64 v[26:27], 11, v[26:27]
	v_cvt_pk_bf16_f32 v34, v41, v39
	v_cvt_pk_bf16_f32 v35, v43, v45
	v_cvt_pk_bf16_f32 v36, v47, v49
	v_cvt_pk_bf16_f32 v37, v51, v55
	v_lshl_add_u64 v[26:27], v[52:53], 0, v[26:27]
	global_store_dwordx4 v[26:27], v[34:37], off nt
	s_waitcnt lgkmcnt(0)
	s_mov_b32 s34, s11

; __device__ __forceinline__ void transpose_item(const float* W, int K, int N, int c0, int ncols, bf16_t* WT, int row_off, float scale, LAS float* scr, int item, int lane) {
;     ...
; #pragma unroll 8
;     for (int i = 0; i < 32; ++i) { const int kk = 2 * i + (lane >> 5); scr[kk * 33 + (lane & 31)] = W[(size_t)(k0 + kk) * N + c0 + n0 + (lane & 31)] * scale; }
;     asm volatile("s_waitcnt lgkmcnt(0)" ::: "memory");
.LBB0_237:
	s_lshl_b32 s35, s0, 1
	s_lshl_b32 s36, s5, 1
	v_or_b32_e32 v36, s36, v2
	s_add_i32 s37, s35, 4
	s_add_i32 s38, s36, 4
	s_add_i32 s39, s35, 8
	s_add_i32 s40, s36, 8
	s_add_i32 s41, s35, 12
	s_add_i32 s44, s36, 12
	s_add_i32 s45, s35, 16
	s_add_i32 s46, s36, 16
	s_add_i32 s47, s35, 20
	s_add_i32 s48, s36, 20
	s_add_i32 s49, s35, 24
	s_add_i32 s50, s36, 24
	s_add_i32 s51, s35, 28
	s_add_i32 s52, s36, 28
	v_or_b32_e32 v34, s35, v5
	v_ashrrev_i32_e32 v37, 31, v36
	v_or_b32_e32 v38, s37, v5
	v_or_b32_e32 v40, s38, v2
	v_or_b32_e32 v42, s39, v5
	v_or_b32_e32 v44, s40, v2
	v_or_b32_e32 v46, s41, v5
	v_or_b32_e32 v48, s44, v2
	v_or_b32_e32 v50, s45, v5
	v_or_b32_e32 v52, s46, v2
	v_or_b32_e32 v54, s47, v5
	v_or_b32_e32 v56, s48, v2
	v_or_b32_e32 v58, s49, v5
	v_or_b32_e32 v60, s50, v2
	v_or_b32_e32 v62, s51, v5
	v_or_b32_e32 v64, s52, v2
	v_ashrrev_i32_e32 v35, 31, v34
	v_lshlrev_b64 v[36:37], 12, v[36:37]
	v_ashrrev_i32_e32 v41, 31, v40
	v_ashrrev_i32_e32 v39, 31, v38
	v_ashrrev_i32_e32 v45, 31, v44
	v_ashrrev_i32_e32 v43, 31, v42
	v_ashrrev_i32_e32 v49, 31, v48
	v_ashrrev_i32_e32 v47, 31, v46
	v_ashrrev_i32_e32 v53, 31, v52
	v_ashrrev_i32_e32 v51, 31, v50
	v_ashrrev_i32_e32 v57, 31, v56
	v_ashrrev_i32_e32 v55, 31, v54
	v_ashrrev_i32_e32 v61, 31, v60
	v_ashrrev_i32_e32 v59, 31, v58
	v_ashrrev_i32_e32 v65, 31, v64
	v_ashrrev_i32_e32 v63, 31, v62
	v_lshlrev_b64 v[34:35], 12, v[34:35]
	v_lshl_add_u64 v[36:37], v[26:27], 0, v[36:37]
	v_lshlrev_b64 v[38:39], 12, v[38:39]
	v_lshlrev_b64 v[40:41], 12, v[40:41]
	v_lshlrev_b64 v[42:43], 12, v[42:43]
	v_lshlrev_b64 v[44:45], 12, v[44:45]
	v_lshlrev_b64 v[46:47], 12, v[46:47]
	v_lshlrev_b64 v[48:49], 12, v[48:49]
	v_lshlrev_b64 v[50:51], 12, v[50:51]
	v_lshlrev_b64 v[52:53], 12, v[52:53]
	v_lshlrev_b64 v[54:55], 12, v[54:55]
	v_lshlrev_b64 v[56:57], 12, v[56:57]
	v_lshlrev_b64 v[58:59], 12, v[58:59]
	v_lshlrev_b64 v[60:61], 12, v[60:61]
	v_lshlrev_b64 v[62:63], 12, v[62:63]
	v_lshlrev_b64 v[64:65], 12, v[64:65]
	v_lshl_add_u64 v[34:35], v[26:27], 0, v[34:35]
	v_lshl_add_u64 v[40:41], v[26:27], 0, v[40:41]
	v_lshl_add_u64 v[38:39], v[26:27], 0, v[38:39]
	v_lshl_add_u64 v[44:45], v[26:27], 0, v[44:45]
	v_lshl_add_u64 v[42:43], v[26:27], 0, v[42:43]
	v_lshl_add_u64 v[48:49], v[26:27], 0, v[48:49]
	v_lshl_add_u64 v[46:47], v[26:27], 0, v[46:47]
	v_lshl_add_u64 v[52:53], v[26:27], 0, v[52:53]
	v_lshl_add_u64 v[50:51], v[26:27], 0, v[50:51]
	v_lshl_add_u64 v[56:57], v[26:27], 0, v[56:57]
	v_lshl_add_u64 v[54:55], v[26:27], 0, v[54:55]
	v_lshl_add_u64 v[60:61], v[26:27], 0, v[60:61]
	v_lshl_add_u64 v[58:59], v[26:27], 0, v[58:59]
	v_lshl_add_u64 v[64:65], v[26:27], 0, v[64:65]
	v_lshl_add_u64 v[62:63], v[26:27], 0, v[62:63]
	global_load_dword v25, v[36:37], off nt
	global_load_dword v28, v[34:35], off nt
	global_load_dword v66, v[40:41], off nt
	global_load_dword v67, v[38:39], off nt
	global_load_dword v68, v[44:45], off nt
	global_load_dword v69, v[42:43], off nt
	global_load_dword v70, v[48:49], off nt
	global_load_dword v71, v[46:47], off nt
	global_load_dword v72, v[52:53], off nt
	global_load_dword v73, v[50:51], off nt
	global_load_dword v74, v[56:57], off nt
	global_load_dword v75, v[54:55], off nt
	global_load_dword v76, v[60:61], off nt
	global_load_dword v77, v[58:59], off nt
	global_load_dword v78, v[64:65], off nt
	global_load_dword v79, v[62:63], off nt
	v_or_b32_e32 v36, s35, v1
	v_or_b32_e32 v34, s36, v0
	s_add_i32 s5, s5, 16
	s_add_i32 s0, s0, 16
	s_add_i32 s29, s29, -16
	v_mad_u64_u32 v[34:35], s[42:43], v34, s31, v[4:5]
	v_mad_u64_u32 v[36:37], s[42:43], v36, s31, v[4:5]
	v_or_b32_e32 v35, s37, v1
	v_or_b32_e32 v37, s38, v0
	v_or_b32_e32 v44, s39, v1
	v_or_b32_e32 v42, s40, v0
	v_or_b32_e32 v48, s41, v1
	v_or_b32_e32 v46, s44, v0
	v_or_b32_e32 v52, s45, v1
	v_or_b32_e32 v50, s46, v0
	v_or_b32_e32 v56, s47, v1
	v_or_b32_e32 v54, s48, v0
	v_or_b32_e32 v60, s49, v1
	v_or_b32_e32 v58, s50, v0
	v_or_b32_e32 v64, s51, v1
	v_or_b32_e32 v62, s52, v0
	s_cmp_lg_u32 s29, 0
	v_mad_u64_u32 v[38:39], s[36:37], v37, s31, v[4:5]
	v_mad_u64_u32 v[40:41], s[36:37], v35, s31, v[4:5]
	v_mad_u64_u32 v[42:43], s[36:37], v42, s31, v[4:5]
	v_mad_u64_u32 v[44:45], s[36:37], v44, s31, v[4:5]
	v_mad_u64_u32 v[46:47], s[36:37], v46, s31, v[4:5]
	v_mad_u64_u32 v[48:49], s[36:37], v48, s31, v[4:5]
	v_mad_u64_u32 v[50:51], s[36:37], v50, s31, v[4:5]
	v_mad_u64_u32 v[52:53], s[36:37], v52, s31, v[4:5]
	v_mad_u64_u32 v[54:55], s[36:37], v54, s31, v[4:5]
	v_mad_u64_u32 v[56:57], s[36:37], v56, s31, v[4:5]
	v_mad_u64_u32 v[58:59], s[36:37], v58, s31, v[4:5]
	v_mad_u64_u32 v[60:61], s[36:37], v60, s31, v[4:5]
	v_mad_u64_u32 v[62:63], s[36:37], v62, s31, v[4:5]
	v_mad_u64_u32 v[64:65], s[36:37], v64, s31, v[4:5]
	s_waitcnt vmcnt(0)
	ds_write_b32 v34, v25
	ds_write_b32 v36, v28
	ds_write_b32 v38, v66
	ds_write_b32 v40, v67
	ds_write_b32 v42, v68
	ds_write_b32 v44, v69
	ds_write_b32 v46, v70
	ds_write_b32 v48, v71
	ds_write_b32 v50, v72
	ds_write_b32 v52, v73
	ds_write_b32 v54, v74
	ds_write_b32 v56, v75
	ds_write_b32 v58, v76
	ds_write_b32 v60, v77
	ds_write_b32 v62, v78
	ds_write_b32 v64, v79
	s_cbranch_scc1 .LBB0_237
; #define LAS __attribute__((address_space(3)))
; __device__ __forceinline__ unsigned cvtpk(float lo, float hi) { return pg8::cvt_pk_bf16(lo, hi); }
; __device__ __forceinline__ void transpose_item(const float* W, int K, int N, int c0, int ncols, bf16_t* WT, int row_off, float scale, LAS float* scr, int item, int lane) {
;     ...
;     const int c = lane & 7;
; #pragma unroll
;     for (int j = 0; j < 4; ++j) { const int n = (lane >> 3) + 8 * j; const LAS float* s = scr + (8 * c) * 33 + n;
;         u32x4 o; o.x = cvtpk(s[0 * 33], s[1 * 33]); o.y = cvtpk(s[2 * 33], s[3 * 33]); o.z = cvtpk(s[4 * 33], s[5 * 33]); o.w = cvtpk(s[6 * 33], s[7 * 33]);
;         *(u32x4*)(WT + (size_t)(row_off + n0 + n) * K + k0 + 8 * c) = o; }
;     asm volatile("s_waitcnt lgkmcnt(0)" ::: "memory");
	s_waitcnt lgkmcnt(0)
	ds_read2_b32 v[26:27], v30 offset0:33 offset1:41
	ds_read2_b32 v[38:39], v30 offset1:8
	ds_read2_b32 v[40:41], v30 offset0:66 offset1:74
	ds_read2_b32 v[42:43], v30 offset0:99 offset1:107
	ds_read2_b32 v[44:45], v30 offset0:132 offset1:140
	ds_read2_b32 v[46:47], v30 offset0:165 offset1:173
	ds_read2_b32 v[48:49], v30 offset0:198 offset1:206
	ds_read2_b32 v[50:51], v30 offset0:231 offset1:239
	v_or_b32_e32 v54, s4, v29
	s_ashr_i32 s29, s28, 31
	v_ashrrev_i32_e32 v55, 31, v54
	v_lshl_add_u64 v[52:53], s[28:29], 1, v[16:17]
	v_lshlrev_b64 v[54:55], 10, v[54:55]
	s_waitcnt lgkmcnt(6)
	v_cvt_pk_bf16_f32 v34, v38, v26
	s_waitcnt lgkmcnt(4)
	v_cvt_pk_bf16_f32 v35, v40, v42
	s_waitcnt lgkmcnt(2)
	v_cvt_pk_bf16_f32 v36, v44, v46
	s_waitcnt lgkmcnt(0)
	v_cvt_pk_bf16_f32 v37, v48, v50
	v_lshl_add_u64 v[54:55], v[52:53], 0, v[54:55]
	v_or_b32_e32 v26, s4, v31
	global_store_dwordx4 v[54:55], v[34:37], off nt
	s_nop 1
	v_cvt_pk_bf16_f32 v34, v39, v27
	v_ashrrev_i32_e32 v27, 31, v26
	v_cvt_pk_bf16_f32 v35, v41, v43
	v_cvt_pk_bf16_f32 v36, v45, v47
	v_cvt_pk_bf16_f32 v37, v49, v51
	v_lshlrev_b64 v[26:27], 10, v[26:27]
	ds_read2_b32 v[38:39], v30 offset0:49 offset1:57
	ds_read2_b32 v[40:41], v30 offset0:16 offset1:24
	ds_read2_b32 v[42:43], v30 offset0:82 offset1:90
	ds_read2_b32 v[44:45], v30 offset0:115 offset1:123
	ds_read2_b32 v[46:47], v30 offset0:148 offset1:156
	ds_read2_b32 v[48:49], v30 offset0:181 offset1:189
	ds_read2_b32 v[50:51], v30 offset0:214 offset1:222
	ds_read2_b32 v[54:55], v30 offset0:247 offset1:255
	v_lshl_add_u64 v[26:27], v[52:53], 0, v[26:27]
	global_store_dwordx4 v[26:27], v[34:37], off nt
	v_or_b32_e32 v26, s4, v32
	v_ashrrev_i32_e32 v27, 31, v26
	v_lshlrev_b64 v[26:27], 10, v[26:27]
	s_waitcnt lgkmcnt(6)
	v_cvt_pk_bf16_f32 v34, v40, v38
	s_waitcnt lgkmcnt(4)
	v_cvt_pk_bf16_f32 v35, v42, v44
	s_waitcnt lgkmcnt(2)
	v_cvt_pk_bf16_f32 v36, v46, v48
	s_waitcnt lgkmcnt(0)
	v_cvt_pk_bf16_f32 v37, v50, v54
	v_lshl_add_u64 v[26:27], v[52:53], 0, v[26:27]
	global_store_dwordx4 v[26:27], v[34:37], off nt
	v_or_b32_e32 v26, s4, v33
	v_ashrrev_i32_e32 v27, 31, v26
	v_lshlrev_b64 v[26:27], 10, v[26:27]
	v_cvt_pk_bf16_f32 v34, v41, v39
	v_cvt_pk_bf16_f32 v35, v43, v45
	v_cvt_pk_bf16_f32 v36, v47, v49
	v_cvt_pk_bf16_f32 v37, v51, v55
	v_lshl_add_u64 v[26:27], v[52:53], 0, v[26:27]
	global_store_dwordx4 v[26:27], v[34:37], off nt
	s_waitcnt lgkmcnt(0)

; __device__ __forceinline__ void transpose_item(const float* W, int K, int N, int c0, int ncols, bf16_t* WT, int row_off, float scale, LAS float* scr, int item, int lane) {
;     ...
; #pragma unroll 8
;     for (int i = 0; i < 32; ++i) { const int kk = 2 * i + (lane >> 5); scr[kk * 33 + (lane & 31)] = W[(size_t)(k0 + kk) * N + c0 + n0 + (lane & 31)] * scale; }
.LBB0_244:
	s_lshl_b32 s35, s0, 1
	s_lshl_b32 s36, s5, 1
	v_or_b32_e32 v36, s36, v2
	s_add_i32 s37, s35, 4
	s_add_i32 s38, s36, 4
	s_add_i32 s39, s35, 8
	s_add_i32 s40, s36, 8
	s_add_i32 s41, s35, 12
	s_add_i32 s44, s36, 12
	s_add_i32 s45, s35, 16
	s_add_i32 s46, s36, 16
	s_add_i32 s47, s35, 20
	s_add_i32 s48, s36, 20
	s_add_i32 s49, s35, 24
	s_add_i32 s50, s36, 24
	s_add_i32 s51, s35, 28
	s_add_i32 s52, s36, 28
	v_or_b32_e32 v34, s35, v5
	v_ashrrev_i32_e32 v37, 31, v36
	v_or_b32_e32 v38, s37, v5
	v_or_b32_e32 v40, s38, v2
	v_or_b32_e32 v42, s39, v5
	v_or_b32_e32 v44, s40, v2
	v_or_b32_e32 v46, s41, v5
	v_or_b32_e32 v48, s44, v2
	v_or_b32_e32 v50, s45, v5
	v_or_b32_e32 v52, s46, v2
	v_or_b32_e32 v54, s47, v5
	v_or_b32_e32 v56, s48, v2
	v_or_b32_e32 v58, s49, v5
	v_or_b32_e32 v60, s50, v2
	v_or_b32_e32 v62, s51, v5
	v_or_b32_e32 v64, s52, v2
	v_ashrrev_i32_e32 v35, 31, v34
	v_lshlrev_b64 v[36:37], 12, v[36:37]
	v_ashrrev_i32_e32 v41, 31, v40
	v_ashrrev_i32_e32 v39, 31, v38
	v_ashrrev_i32_e32 v45, 31, v44
	v_ashrrev_i32_e32 v43, 31, v42
	v_ashrrev_i32_e32 v49, 31, v48
	v_ashrrev_i32_e32 v47, 31, v46
	v_ashrrev_i32_e32 v53, 31, v52
	v_ashrrev_i32_e32 v51, 31, v50
	v_ashrrev_i32_e32 v57, 31, v56
	v_ashrrev_i32_e32 v55, 31, v54
	v_ashrrev_i32_e32 v61, 31, v60
	v_ashrrev_i32_e32 v59, 31, v58
	v_ashrrev_i32_e32 v65, 31, v64
	v_ashrrev_i32_e32 v63, 31, v62
	v_lshlrev_b64 v[34:35], 12, v[34:35]
	v_lshl_add_u64 v[36:37], v[26:27], 0, v[36:37]
	v_lshlrev_b64 v[38:39], 12, v[38:39]
	v_lshlrev_b64 v[40:41], 12, v[40:41]
	v_lshlrev_b64 v[42:43], 12, v[42:43]
	v_lshlrev_b64 v[44:45], 12, v[44:45]
	v_lshlrev_b64 v[46:47], 12, v[46:47]
	v_lshlrev_b64 v[48:49], 12, v[48:49]
	v_lshlrev_b64 v[50:51], 12, v[50:51]
	v_lshlrev_b64 v[52:53], 12, v[52:53]
	v_lshlrev_b64 v[54:55], 12, v[54:55]
	v_lshlrev_b64 v[56:57], 12, v[56:57]
	v_lshlrev_b64 v[58:59], 12, v[58:59]
	v_lshlrev_b64 v[60:61], 12, v[60:61]
	v_lshlrev_b64 v[62:63], 12, v[62:63]
	v_lshlrev_b64 v[64:65], 12, v[64:65]
	v_lshl_add_u64 v[34:35], v[26:27], 0, v[34:35]
	v_lshl_add_u64 v[40:41], v[26:27], 0, v[40:41]
	v_lshl_add_u64 v[38:39], v[26:27], 0, v[38:39]
	v_lshl_add_u64 v[44:45], v[26:27], 0, v[44:45]
	v_lshl_add_u64 v[42:43], v[26:27], 0, v[42:43]
	v_lshl_add_u64 v[48:49], v[26:27], 0, v[48:49]
	v_lshl_add_u64 v[46:47], v[26:27], 0, v[46:47]
	v_lshl_add_u64 v[52:53], v[26:27], 0, v[52:53]
	v_lshl_add_u64 v[50:51], v[26:27], 0, v[50:51]
	v_lshl_add_u64 v[56:57], v[26:27], 0, v[56:57]
	v_lshl_add_u64 v[54:55], v[26:27], 0, v[54:55]
	v_lshl_add_u64 v[60:61], v[26:27], 0, v[60:61]
	v_lshl_add_u64 v[58:59], v[26:27], 0, v[58:59]
	v_lshl_add_u64 v[64:65], v[26:27], 0, v[64:65]
	v_lshl_add_u64 v[62:63], v[26:27], 0, v[62:63]
	global_load_dword v25, v[36:37], off nt
	global_load_dword v28, v[34:35], off nt
	global_load_dword v66, v[40:41], off nt
	global_load_dword v67, v[38:39], off nt
	global_load_dword v68, v[44:45], off nt
	global_load_dword v69, v[42:43], off nt
	global_load_dword v70, v[48:49], off nt
	global_load_dword v71, v[46:47], off nt
	global_load_dword v72, v[52:53], off nt
	global_load_dword v73, v[50:51], off nt
	global_load_dword v74, v[56:57], off nt
	global_load_dword v75, v[54:55], off nt
	global_load_dword v76, v[60:61], off nt
	global_load_dword v77, v[58:59], off nt
	global_load_dword v78, v[64:65], off nt
	global_load_dword v79, v[62:63], off nt
	v_or_b32_e32 v36, s35, v1
	v_or_b32_e32 v34, s36, v0
	s_add_i32 s5, s5, 16
	s_add_i32 s0, s0, 16
	s_add_i32 s29, s29, -16
	v_mad_u64_u32 v[34:35], s[42:43], v34, s31, v[4:5]
	v_mad_u64_u32 v[36:37], s[42:43], v36, s31, v[4:5]
	v_or_b32_e32 v35, s37, v1
	v_or_b32_e32 v37, s38, v0
	v_or_b32_e32 v44, s39, v1
	v_or_b32_e32 v42, s40, v0
	v_or_b32_e32 v48, s41, v1
	v_or_b32_e32 v46, s44, v0
	v_or_b32_e32 v52, s45, v1
	v_or_b32_e32 v50, s46, v0
	v_or_b32_e32 v56, s47, v1
	v_or_b32_e32 v54, s48, v0
	v_or_b32_e32 v60, s49, v1
	v_or_b32_e32 v58, s50, v0
	v_or_b32_e32 v64, s51, v1
	v_or_b32_e32 v62, s52, v0
	s_cmp_lg_u32 s29, 0
	v_mad_u64_u32 v[38:39], s[36:37], v37, s31, v[4:5]
	v_mad_u64_u32 v[40:41], s[36:37], v35, s31, v[4:5]
	v_mad_u64_u32 v[42:43], s[36:37], v42, s31, v[4:5]
	v_mad_u64_u32 v[44:45], s[36:37], v44, s31, v[4:5]
	v_mad_u64_u32 v[46:47], s[36:37], v46, s31, v[4:5]
	v_mad_u64_u32 v[48:49], s[36:37], v48, s31, v[4:5]
	v_mad_u64_u32 v[50:51], s[36:37], v50, s31, v[4:5]
	v_mad_u64_u32 v[52:53], s[36:37], v52, s31, v[4:5]
	v_mad_u64_u32 v[54:55], s[36:37], v54, s31, v[4:5]
	v_mad_u64_u32 v[56:57], s[36:37], v56, s31, v[4:5]
	v_mad_u64_u32 v[58:59], s[36:37], v58, s31, v[4:5]
	v_mad_u64_u32 v[60:61], s[36:37], v60, s31, v[4:5]
	v_mad_u64_u32 v[62:63], s[36:37], v62, s31, v[4:5]
	v_mad_u64_u32 v[64:65], s[36:37], v64, s31, v[4:5]
	s_waitcnt vmcnt(0)
	ds_write_b32 v34, v25
	ds_write_b32 v36, v28
	ds_write_b32 v38, v66
	ds_write_b32 v40, v67
	ds_write_b32 v42, v68
	ds_write_b32 v44, v69
	ds_write_b32 v46, v70
	ds_write_b32 v48, v71
	ds_write_b32 v50, v72
	ds_write_b32 v52, v73
	ds_write_b32 v54, v74
	ds_write_b32 v56, v75
	ds_write_b32 v58, v76
	ds_write_b32 v60, v77
	ds_write_b32 v62, v78
	ds_write_b32 v64, v79
	s_cbranch_scc1 .LBB0_244
; #define LAS __attribute__((address_space(3)))
; __device__ __forceinline__ unsigned cvtpk(float lo, float hi) { return pg8::cvt_pk_bf16(lo, hi); }
; __device__ __forceinline__ void transpose_item(const float* W, int K, int N, int c0, int ncols, bf16_t* WT, int row_off, float scale, LAS float* scr, int item, int lane) {
;     ...
;     const int c = lane & 7;
; #pragma unroll
;     for (int j = 0; j < 4; ++j) { const int n = (lane >> 3) + 8 * j; const LAS float* s = scr + (8 * c) * 33 + n;
;         u32x4 o; o.x = cvtpk(s[0 * 33], s[1 * 33]); o.y = cvtpk(s[2 * 33], s[3 * 33]); o.z = cvtpk(s[4 * 33], s[5 * 33]); o.w = cvtpk(s[6 * 33], s[7 * 33]);
;         *(u32x4*)(WT + (size_t)(row_off + n0 + n) * K + k0 + 8 * c) = o; }
;     asm volatile("s_waitcnt lgkmcnt(0)" ::: "memory");
	s_waitcnt lgkmcnt(0)
	ds_read2_b32 v[26:27], v30 offset0:33 offset1:41
	ds_read2_b32 v[38:39], v30 offset1:8
	ds_read2_b32 v[40:41], v30 offset0:66 offset1:74
	ds_read2_b32 v[42:43], v30 offset0:99 offset1:107
	ds_read2_b32 v[44:45], v30 offset0:132 offset1:140
	ds_read2_b32 v[46:47], v30 offset0:165 offset1:173
	ds_read2_b32 v[48:49], v30 offset0:198 offset1:206
	ds_read2_b32 v[50:51], v30 offset0:231 offset1:239
	v_or_b32_e32 v54, s4, v29
	s_ashr_i32 s29, s28, 31
	v_ashrrev_i32_e32 v55, 31, v54
	v_lshl_add_u64 v[52:53], s[28:29], 1, v[18:19]
	v_lshlrev_b64 v[54:55], 11, v[54:55]
	s_waitcnt lgkmcnt(6)
	v_cvt_pk_bf16_f32 v34, v38, v26
	s_waitcnt lgkmcnt(4)
	v_cvt_pk_bf16_f32 v35, v40, v42
	s_waitcnt lgkmcnt(2)
	v_cvt_pk_bf16_f32 v36, v44, v46
	s_waitcnt lgkmcnt(0)
	v_cvt_pk_bf16_f32 v37, v48, v50
	v_lshl_add_u64 v[54:55], v[52:53], 0, v[54:55]
	v_or_b32_e32 v26, s4, v31
	global_store_dwordx4 v[54:55], v[34:37], off nt
	s_nop 1
	v_cvt_pk_bf16_f32 v34, v39, v27
	v_ashrrev_i32_e32 v27, 31, v26
	v_cvt_pk_bf16_f32 v35, v41, v43
	v_cvt_pk_bf16_f32 v36, v45, v47
	v_cvt_pk_bf16_f32 v37, v49, v51
	v_lshlrev_b64 v[26:27], 11, v[26:27]
	ds_read2_b32 v[38:39], v30 offset0:49 offset1:57
	ds_read2_b32 v[40:41], v30 offset0:16 offset1:24
	ds_read2_b32 v[42:43], v30 offset0:82 offset1:90
	ds_read2_b32 v[44:45], v30 offset0:115 offset1:123
	ds_read2_b32 v[46:47], v30 offset0:148 offset1:156
	ds_read2_b32 v[48:49], v30 offset0:181 offset1:189
	ds_read2_b32 v[50:51], v30 offset0:214 offset1:222
	ds_read2_b32 v[54:55], v30 offset0:247 offset1:255
	v_lshl_add_u64 v[26:27], v[52:53], 0, v[26:27]
	global_store_dwordx4 v[26:27], v[34:37], off nt
	v_or_b32_e32 v26, s4, v32
	v_ashrrev_i32_e32 v27, 31, v26
	v_lshlrev_b64 v[26:27], 11, v[26:27]
	s_waitcnt lgkmcnt(6)
	v_cvt_pk_bf16_f32 v34, v40, v38
	s_waitcnt lgkmcnt(4)
	v_cvt_pk_bf16_f32 v35, v42, v44
	s_waitcnt lgkmcnt(2)
	v_cvt_pk_bf16_f32 v36, v46, v48
	s_waitcnt lgkmcnt(0)
	v_cvt_pk_bf16_f32 v37, v50, v54
	v_lshl_add_u64 v[26:27], v[52:53], 0, v[26:27]
	global_store_dwordx4 v[26:27], v[34:37], off nt
	v_or_b32_e32 v26, s4, v33
	v_ashrrev_i32_e32 v27, 31, v26
	v_lshlrev_b64 v[26:27], 11, v[26:27]
	v_cvt_pk_bf16_f32 v34, v41, v39
	v_cvt_pk_bf16_f32 v35, v43, v45
	v_cvt_pk_bf16_f32 v36, v47, v49
	v_cvt_pk_bf16_f32 v37, v51, v55
	v_lshl_add_u64 v[26:27], v[52:53], 0, v[26:27]
	global_store_dwordx4 v[26:27], v[34:37], off nt
	s_waitcnt lgkmcnt(0)

; __device__ __forceinline__ void transpose_item(const float* W, int K, int N, int c0, int ncols, bf16_t* WT, int row_off, float scale, LAS float* scr, int item, int lane) {
;     ...
; #pragma unroll 8
;     for (int i = 0; i < 32; ++i) { const int kk = 2 * i + (lane >> 5); scr[kk * 33 + (lane & 31)] = W[(size_t)(k0 + kk) * N + c0 + n0 + (lane & 31)] * scale; }
.LBB0_251:
	s_lshl_b32 s28, s3, 1
	s_lshl_b32 s29, s0, 1
	v_or_b32_e32 v2, s29, v28
	s_add_i32 s35, s28, 4
	s_add_i32 s36, s29, 4
	v_mov_b32_e32 v37, v3
	s_add_i32 s38, s29, 8
	v_lshlrev_b64 v[50:51], 12, v[2:3]
	v_or_b32_e32 v36, s35, v5
	v_or_b32_e32 v2, s36, v28
	v_mov_b32_e32 v35, v3
	v_or_b32_e32 v34, s28, v5
	s_add_i32 s40, s29, 12
	v_lshlrev_b64 v[36:37], 12, v[36:37]
	v_lshlrev_b64 v[52:53], 12, v[2:3]
	v_or_b32_e32 v2, s38, v28
	s_add_i32 s37, s28, 8
	s_add_i32 s39, s28, 12
	s_add_i32 s42, s29, 16
	v_lshlrev_b64 v[34:35], 12, v[34:35]
	v_lshl_add_u64 v[50:51], v[26:27], 0, v[50:51]
	v_lshl_add_u64 v[36:37], v[26:27], 0, v[36:37]
	v_lshlrev_b64 v[54:55], 12, v[2:3]
	v_or_b32_e32 v2, s40, v28
	v_mov_b32_e32 v39, v3
	v_mov_b32_e32 v41, v3
	s_add_i32 s44, s29, 20
	v_or_b32_e32 v38, s37, v5
	v_or_b32_e32 v40, s39, v5
	v_lshl_add_u64 v[34:35], v[26:27], 0, v[34:35]
	v_lshl_add_u64 v[52:53], v[26:27], 0, v[52:53]
	global_load_dword v25, v[50:51], off nt
	global_load_dword v66, v[34:35], off nt
	global_load_dword v67, v[52:53], off nt
	global_load_dword v68, v[36:37], off nt
	v_lshlrev_b64 v[36:37], 12, v[2:3]
	v_or_b32_e32 v2, s42, v28
	s_add_i32 s41, s28, 16
	s_add_i32 s43, s28, 20
	s_add_i32 s46, s29, 24
	v_lshlrev_b64 v[38:39], 12, v[38:39]
	v_lshlrev_b64 v[40:41], 12, v[40:41]
	v_lshl_add_u64 v[34:35], v[26:27], 0, v[54:55]
	v_lshl_add_u64 v[36:37], v[26:27], 0, v[36:37]
	v_lshlrev_b64 v[50:51], 12, v[2:3]
	v_or_b32_e32 v2, s44, v28
	v_mov_b32_e32 v43, v3
	v_mov_b32_e32 v45, v3
	s_add_i32 s45, s28, 24
	s_add_i32 s47, s28, 28
	s_add_i32 s48, s29, 28
	v_or_b32_e32 v42, s41, v5
	v_or_b32_e32 v44, s43, v5
	v_lshl_add_u64 v[38:39], v[26:27], 0, v[38:39]
	v_lshl_add_u64 v[40:41], v[26:27], 0, v[40:41]
	global_load_dword v69, v[34:35], off nt
	global_load_dword v70, v[38:39], off nt
	global_load_dword v71, v[36:37], off nt
	global_load_dword v72, v[40:41], off nt
	v_lshlrev_b64 v[36:37], 12, v[2:3]
	v_or_b32_e32 v2, s46, v28
	v_mov_b32_e32 v47, v3
	v_mov_b32_e32 v49, v3
	v_or_b32_e32 v46, s45, v5
	v_or_b32_e32 v48, s47, v5
	v_lshlrev_b64 v[42:43], 12, v[42:43]
	v_lshlrev_b64 v[44:45], 12, v[44:45]
	v_lshl_add_u64 v[34:35], v[26:27], 0, v[50:51]
	v_lshl_add_u64 v[36:37], v[26:27], 0, v[36:37]
	v_lshlrev_b64 v[38:39], 12, v[2:3]
	v_or_b32_e32 v2, s48, v28
	v_lshlrev_b64 v[46:47], 12, v[46:47]
	v_lshlrev_b64 v[48:49], 12, v[48:49]
	v_lshl_add_u64 v[42:43], v[26:27], 0, v[42:43]
	v_lshl_add_u64 v[44:45], v[26:27], 0, v[44:45]
	global_load_dword v73, v[34:35], off nt
	global_load_dword v74, v[42:43], off nt
	global_load_dword v75, v[36:37], off nt
	global_load_dword v76, v[44:45], off nt
	v_lshl_add_u64 v[34:35], v[26:27], 0, v[38:39]
	v_lshlrev_b64 v[36:37], 12, v[2:3]
	v_lshl_add_u64 v[46:47], v[26:27], 0, v[46:47]
	v_lshl_add_u64 v[48:49], v[26:27], 0, v[48:49]
	v_lshl_add_u64 v[36:37], v[26:27], 0, v[36:37]
	global_load_dword v2, v[34:35], off nt
	global_load_dword v77, v[46:47], off nt
	global_load_dword v78, v[36:37], off nt
	global_load_dword v79, v[48:49], off nt
	v_or_b32_e32 v36, s28, v1
	v_or_b32_e32 v34, s29, v0
	s_add_i32 s0, s0, 16
	s_add_i32 s3, s3, 16
	s_add_i32 s5, s5, -16
	v_mad_u64_u32 v[34:35], s[28:29], v34, s31, v[4:5]
	v_mad_u64_u32 v[36:37], s[28:29], v36, s31, v[4:5]
	v_or_b32_e32 v35, s35, v1
	v_or_b32_e32 v37, s36, v0
	v_or_b32_e32 v44, s37, v1
	v_or_b32_e32 v42, s38, v0
	v_or_b32_e32 v48, s39, v1
	v_or_b32_e32 v46, s40, v0
	v_or_b32_e32 v52, s41, v1
	v_or_b32_e32 v50, s42, v0
	v_or_b32_e32 v56, s43, v1
	v_or_b32_e32 v54, s44, v0
	v_or_b32_e32 v60, s45, v1
	v_or_b32_e32 v58, s46, v0
	v_or_b32_e32 v64, s47, v1
	v_or_b32_e32 v62, s48, v0
	s_cmp_lg_u32 s5, 0
	v_mad_u64_u32 v[38:39], s[28:29], v37, s31, v[4:5]
	v_mad_u64_u32 v[40:41], s[28:29], v35, s31, v[4:5]
	v_mad_u64_u32 v[42:43], s[28:29], v42, s31, v[4:5]
	v_mad_u64_u32 v[44:45], s[28:29], v44, s31, v[4:5]
	v_mad_u64_u32 v[46:47], s[28:29], v46, s31, v[4:5]
	v_mad_u64_u32 v[48:49], s[28:29], v48, s31, v[4:5]
	v_mad_u64_u32 v[50:51], s[28:29], v50, s31, v[4:5]
	v_mad_u64_u32 v[52:53], s[28:29], v52, s31, v[4:5]
	v_mad_u64_u32 v[54:55], s[28:29], v54, s31, v[4:5]
	v_mad_u64_u32 v[56:57], s[28:29], v56, s31, v[4:5]
	v_mad_u64_u32 v[58:59], s[28:29], v58, s31, v[4:5]
	v_mad_u64_u32 v[60:61], s[28:29], v60, s31, v[4:5]
	v_mad_u64_u32 v[62:63], s[28:29], v62, s31, v[4:5]
	v_mad_u64_u32 v[64:65], s[28:29], v64, s31, v[4:5]
	s_waitcnt vmcnt(0)
	ds_write_b32 v34, v25
	ds_write_b32 v36, v66
	ds_write_b32 v38, v67
	ds_write_b32 v40, v68
	ds_write_b32 v42, v69
	ds_write_b32 v44, v70
	ds_write_b32 v46, v71
	ds_write_b32 v48, v72
	ds_write_b32 v50, v73
	ds_write_b32 v52, v74
	ds_write_b32 v54, v75
	ds_write_b32 v56, v76
	ds_write_b32 v58, v2
	ds_write_b32 v60, v77
	ds_write_b32 v62, v78
	ds_write_b32 v64, v79
	s_cbranch_scc1 .LBB0_251
; #define LAS __attribute__((address_space(3)))
; __device__ __forceinline__ unsigned cvtpk(float lo, float hi) { return pg8::cvt_pk_bf16(lo, hi); }
; #define SEG(W, K, N, c0, nc, WT, ro, sc) { constexpr int n_ = ((K) / 64) * ((nc) / 32); if (r < n_) { transpose_item(W, K, N, c0, nc, WT, ro, sc, scr, r, lane); continue; } r -= n_; }
; __device__ __forceinline__ void transpose_item(const float* W, int K, int N, int c0, int ncols, bf16_t* WT, int row_off, float scale, LAS float* scr, int item, int lane) {
;     ...
;     const int c = lane & 7;
; #pragma unroll
;     for (int j = 0; j < 4; ++j) { const int n = (lane >> 3) + 8 * j; const LAS float* s = scr + (8 * c) * 33 + n;
;         u32x4 o; o.x = cvtpk(s[0 * 33], s[1 * 33]); o.y = cvtpk(s[2 * 33], s[3 * 33]); o.z = cvtpk(s[4 * 33], s[5 * 33]); o.w = cvtpk(s[6 * 33], s[7 * 33]);
;         *(u32x4*)(WT + (size_t)(row_off + n0 + n) * K + k0 + 8 * c) = o; }
;     asm volatile("s_waitcnt lgkmcnt(0)" ::: "memory");
; __device__ __forceinline__ void p0_prep(const Ptrs& P, LAS unsigned char* lds, int vcu, int G, int wave, int lane, int tid, int part) {
;     ...
;         SEG(P.w_down, 2816, 1024, 0, 1024, (bf16_t*)(P.ws + WS_WDN), 0, 1.f)
	s_waitcnt lgkmcnt(0)
	ds_read2_b32 v[26:27], v30 offset0:33 offset1:41
	ds_read2_b32 v[38:39], v30 offset1:8
	ds_read2_b32 v[40:41], v30 offset0:66 offset1:74
	ds_read2_b32 v[42:43], v30 offset0:99 offset1:107
	ds_read2_b32 v[44:45], v30 offset0:132 offset1:140
	ds_read2_b32 v[46:47], v30 offset0:165 offset1:173
	ds_read2_b32 v[48:49], v30 offset0:198 offset1:206
	ds_read2_b32 v[50:51], v30 offset0:231 offset1:239
	v_or_b32_e32 v2, s2, v29
	s_lshl_b32 s0, s4, 1
	v_mul_u32_u24_e32 v2, 0xb00, v2
	v_lshl_add_u64 v[52:53], v[20:21], 0, s[0:1]
	v_lshlrev_b32_e32 v2, 1, v2
	v_lshl_add_u64 v[54:55], v[52:53], 0, v[2:3]
	v_or_b32_e32 v2, s2, v31
	s_waitcnt lgkmcnt(6)
	v_cvt_pk_bf16_f32 v34, v38, v26
	s_waitcnt lgkmcnt(4)
	v_cvt_pk_bf16_f32 v35, v40, v42
	s_waitcnt lgkmcnt(2)
	v_cvt_pk_bf16_f32 v36, v44, v46
	s_waitcnt lgkmcnt(0)
	v_cvt_pk_bf16_f32 v37, v48, v50
	v_mul_u32_u24_e32 v2, 0xb00, v2
	global_store_dwordx4 v[54:55], v[34:37], off nt
	v_lshlrev_b32_e32 v2, 1, v2
	s_nop 0
	v_cvt_pk_bf16_f32 v34, v39, v27
	v_cvt_pk_bf16_f32 v35, v41, v43
	v_cvt_pk_bf16_f32 v36, v45, v47
	v_cvt_pk_bf16_f32 v37, v49, v51
	v_lshl_add_u64 v[26:27], v[52:53], 0, v[2:3]
	ds_read2_b32 v[38:39], v30 offset0:16 offset1:24
	ds_read2_b32 v[40:41], v30 offset0:49 offset1:57
	ds_read2_b32 v[42:43], v30 offset0:82 offset1:90
	ds_read2_b32 v[44:45], v30 offset0:115 offset1:123
	ds_read2_b32 v[46:47], v30 offset0:148 offset1:156
	ds_read2_b32 v[48:49], v30 offset0:181 offset1:189
	ds_read2_b32 v[50:51], v30 offset0:214 offset1:222
	ds_read2_b32 v[54:55], v30 offset0:247 offset1:255
	v_or_b32_e32 v2, s2, v32
	v_mul_u32_u24_e32 v2, 0xb00, v2
	v_lshlrev_b32_e32 v2, 1, v2
	global_store_dwordx4 v[26:27], v[34:37], off nt
	v_lshl_add_u64 v[26:27], v[52:53], 0, v[2:3]
	v_or_b32_e32 v2, s2, v33
	v_mul_u32_u24_e32 v2, 0xb00, v2
	s_waitcnt lgkmcnt(6)
	v_cvt_pk_bf16_f32 v34, v38, v40
	s_waitcnt lgkmcnt(4)
	v_cvt_pk_bf16_f32 v35, v42, v44
	s_waitcnt lgkmcnt(2)
	v_cvt_pk_bf16_f32 v36, v46, v48
	s_waitcnt lgkmcnt(0)
	v_cvt_pk_bf16_f32 v37, v50, v54
	v_lshlrev_b32_e32 v2, 1, v2
	global_store_dwordx4 v[26:27], v[34:37], off nt
	v_lshl_add_u64 v[26:27], v[52:53], 0, v[2:3]
	s_mov_b64 s[2:3], 0
	v_cvt_pk_bf16_f32 v34, v39, v41
	v_cvt_pk_bf16_f32 v35, v43, v45
	v_cvt_pk_bf16_f32 v36, v47, v49
	v_cvt_pk_bf16_f32 v37, v51, v55
	global_store_dwordx4 v[26:27], v[34:37], off nt
	s_waitcnt lgkmcnt(0)

; #define LAS __attribute__((address_space(3)))
; __device__ __forceinline__ unsigned cvtpk(float lo, float hi) { return pg8::cvt_pk_bf16(lo, hi); }
; __device__ __forceinline__ void transpose_item(const float* W, int K, int N, int c0, int ncols, bf16_t* WT, int row_off, float scale, LAS float* scr, int item, int lane) {
;     ...
; #pragma unroll 8
;     for (int i = 0; i < 32; ++i) { const int kk = 2 * i + (lane >> 5); scr[kk * 33 + (lane & 31)] = W[(size_t)(k0 + kk) * N + c0 + n0 + (lane & 31)] * scale; }
;     asm volatile("s_waitcnt lgkmcnt(0)" ::: "memory");
;     const int c = lane & 7;
; #pragma unroll
;     for (int j = 0; j < 4; ++j) { const int n = (lane >> 3) + 8 * j; const LAS float* s = scr + (8 * c) * 33 + n;
;         u32x4 o; o.x = cvtpk(s[0 * 33], s[1 * 33]); o.y = cvtpk(s[2 * 33], s[3 * 33]); o.z = cvtpk(s[4 * 33], s[5 * 33]); o.w = cvtpk(s[6 * 33], s[7 * 33]);
;         *(u32x4*)(WT + (size_t)(row_off + n0 + n) * K + k0 + 8 * c) = o; }
;     asm volatile("s_waitcnt lgkmcnt(0)" ::: "memory");
; __device__ __forceinline__ void p0_prep(const Ptrs& P, LAS unsigned char* lds, int vcu, int G, int wave, int lane, int tid, int part) {
;     ...
;         if (r < 2816) { const int seg = r >> 6, sub = r & 63, pn = seg >> 1, bj = seg & 1;
;             transpose_item(P.w_up, 1024, 5632, bj * 2816 + 128 * pn, 128, (bf16_t*)(P.ws + WS_WUP), 256 * pn + 128 * bj, 1.f, scr, sub, lane); continue; } r -= 2816;
.LBB0_255:
	s_lshl_b32 s29, s4, 1
	s_lshl_b32 s35, s5, 1
	v_or_b32_e32 v25, s29, v5
	v_or_b32_e32 v28, s35, v2
	s_add_i32 s38, s29, 4
	s_add_i32 s39, s35, 4
	s_add_i32 s40, s29, 8
	s_add_i32 s41, s35, 8
	s_add_i32 s42, s29, 12
	s_add_i32 s43, s35, 12
	s_add_i32 s44, s29, 16
	s_add_i32 s45, s35, 16
	s_add_i32 s46, s29, 20
	s_add_i32 s47, s35, 20
	s_add_i32 s48, s29, 24
	s_add_i32 s49, s35, 24
	s_add_i32 s50, s29, 28
	s_add_i32 s51, s35, 28
	v_mad_u64_u32 v[34:35], s[36:37], v28, s33, v[26:27]
	v_mad_u64_u32 v[36:37], s[36:37], v25, s33, v[26:27]
	v_or_b32_e32 v25, s38, v5
	v_or_b32_e32 v28, s39, v2
	v_or_b32_e32 v44, s40, v5
	v_or_b32_e32 v42, s41, v2
	v_or_b32_e32 v48, s42, v5
	v_or_b32_e32 v46, s43, v2
	v_or_b32_e32 v52, s44, v5
	v_or_b32_e32 v50, s45, v2
	v_or_b32_e32 v56, s46, v5
	v_or_b32_e32 v54, s47, v2
	v_or_b32_e32 v60, s48, v5
	v_or_b32_e32 v58, s49, v2
	v_or_b32_e32 v64, s50, v5
	v_or_b32_e32 v62, s51, v2
	v_mad_u64_u32 v[38:39], s[36:37], v28, s33, v[26:27]
	v_mad_u64_u32 v[40:41], s[36:37], v25, s33, v[26:27]
	v_mad_u64_u32 v[42:43], s[36:37], v42, s33, v[26:27]
	v_mad_u64_u32 v[44:45], s[36:37], v44, s33, v[26:27]
	v_mad_u64_u32 v[46:47], s[36:37], v46, s33, v[26:27]
	v_mad_u64_u32 v[48:49], s[36:37], v48, s33, v[26:27]
	v_mad_u64_u32 v[50:51], s[36:37], v50, s33, v[26:27]
	v_mad_u64_u32 v[52:53], s[36:37], v52, s33, v[26:27]
	v_mad_u64_u32 v[54:55], s[36:37], v54, s33, v[26:27]
	v_mad_u64_u32 v[56:57], s[36:37], v56, s33, v[26:27]
	v_mad_u64_u32 v[58:59], s[36:37], v58, s33, v[26:27]
	v_mad_u64_u32 v[60:61], s[36:37], v60, s33, v[26:27]
	v_mad_u64_u32 v[62:63], s[36:37], v62, s33, v[26:27]
	v_mad_u64_u32 v[64:65], s[36:37], v64, s33, v[26:27]
	global_load_dword v25, v[34:35], off nt
	global_load_dword v28, v[36:37], off nt
	global_load_dword v66, v[38:39], off nt
	global_load_dword v67, v[40:41], off nt
	global_load_dword v68, v[42:43], off nt
	global_load_dword v69, v[44:45], off nt
	global_load_dword v70, v[46:47], off nt
	global_load_dword v71, v[48:49], off nt
	global_load_dword v72, v[50:51], off nt
	global_load_dword v73, v[52:53], off nt
	global_load_dword v74, v[54:55], off nt
	global_load_dword v75, v[56:57], off nt
	global_load_dword v76, v[58:59], off nt
	global_load_dword v77, v[60:61], off nt
	global_load_dword v78, v[62:63], off nt
	global_load_dword v79, v[64:65], off nt
	v_or_b32_e32 v36, s29, v1
	v_or_b32_e32 v34, s35, v0
	s_add_i32 s5, s5, 16
	s_add_i32 s4, s4, 16
	s_add_i32 s28, s28, -16
	v_mad_u64_u32 v[34:35], s[36:37], v34, s31, v[4:5]
	v_mad_u64_u32 v[36:37], s[36:37], v36, s31, v[4:5]
	v_or_b32_e32 v35, s38, v1
	v_or_b32_e32 v37, s39, v0
	v_or_b32_e32 v44, s40, v1
	v_or_b32_e32 v42, s41, v0
	v_or_b32_e32 v48, s42, v1
	v_or_b32_e32 v46, s43, v0
	v_or_b32_e32 v52, s44, v1
	v_or_b32_e32 v50, s45, v0
	v_or_b32_e32 v56, s46, v1
	v_or_b32_e32 v54, s47, v0
	v_or_b32_e32 v60, s48, v1
	v_or_b32_e32 v58, s49, v0
	v_or_b32_e32 v64, s50, v1
	v_or_b32_e32 v62, s51, v0
	s_cmp_lg_u32 s28, 0
	v_mad_u64_u32 v[38:39], s[36:37], v37, s31, v[4:5]
	v_mad_u64_u32 v[40:41], s[36:37], v35, s31, v[4:5]
	v_mad_u64_u32 v[42:43], s[36:37], v42, s31, v[4:5]
	v_mad_u64_u32 v[44:45], s[36:37], v44, s31, v[4:5]
	v_mad_u64_u32 v[46:47], s[36:37], v46, s31, v[4:5]
	v_mad_u64_u32 v[48:49], s[36:37], v48, s31, v[4:5]
	v_mad_u64_u32 v[50:51], s[36:37], v50, s31, v[4:5]
	v_mad_u64_u32 v[52:53], s[36:37], v52, s31, v[4:5]
	v_mad_u64_u32 v[54:55], s[36:37], v54, s31, v[4:5]
	v_mad_u64_u32 v[56:57], s[36:37], v56, s31, v[4:5]
	v_mad_u64_u32 v[58:59], s[36:37], v58, s31, v[4:5]
	v_mad_u64_u32 v[60:61], s[36:37], v60, s31, v[4:5]
	v_mad_u64_u32 v[62:63], s[36:37], v62, s31, v[4:5]
	v_mad_u64_u32 v[64:65], s[36:37], v64, s31, v[4:5]
	s_waitcnt vmcnt(0)
	ds_write_b32 v34, v25
	ds_write_b32 v36, v28
	ds_write_b32 v38, v66
	ds_write_b32 v40, v67
	ds_write_b32 v42, v68
	ds_write_b32 v44, v69
	ds_write_b32 v46, v70
	ds_write_b32 v48, v71
	ds_write_b32 v50, v72
	ds_write_b32 v52, v73
	ds_write_b32 v54, v74
	ds_write_b32 v56, v75
	ds_write_b32 v58, v76
	ds_write_b32 v60, v77
	ds_write_b32 v62, v78
	ds_write_b32 v64, v79
	s_cbranch_scc1 .LBB0_255
	s_lshl_b32 s4, s34, 1
	s_lshl_b32 s0, s0, 7
	s_and_b32 s4, s4, 0xffffff00
	s_waitcnt lgkmcnt(0)
	s_or_b32 s0, s0, s4
	ds_read2_b32 v[26:27], v30 offset0:33 offset1:41
	ds_read2_b32 v[38:39], v30 offset1:8
	ds_read2_b32 v[40:41], v30 offset0:66 offset1:74
	ds_read2_b32 v[42:43], v30 offset0:99 offset1:107
	ds_read2_b32 v[44:45], v30 offset0:132 offset1:140
	ds_read2_b32 v[46:47], v30 offset0:165 offset1:173
	ds_read2_b32 v[48:49], v30 offset0:198 offset1:206
	ds_read2_b32 v[50:51], v30 offset0:231 offset1:239
	s_or_b32 s3, s0, s3
	v_or_b32_e32 v54, s3, v29
	s_lshl_b32 s0, s2, 1
	v_ashrrev_i32_e32 v55, 31, v54
	v_lshl_add_u64 v[52:53], v[22:23], 0, s[0:1]
	v_lshlrev_b64 v[54:55], 11, v[54:55]
	s_waitcnt lgkmcnt(6)
	v_cvt_pk_bf16_f32 v34, v38, v26
	s_waitcnt lgkmcnt(4)
	v_cvt_pk_bf16_f32 v35, v40, v42
	s_waitcnt lgkmcnt(2)
	v_cvt_pk_bf16_f32 v36, v44, v46
	s_waitcnt lgkmcnt(0)
	v_cvt_pk_bf16_f32 v37, v48, v50
	v_lshl_add_u64 v[54:55], v[52:53], 0, v[54:55]
	v_or_b32_e32 v26, s3, v31
	global_store_dwordx4 v[54:55], v[34:37], off nt
	s_nop 1
	v_cvt_pk_bf16_f32 v34, v39, v27
	v_ashrrev_i32_e32 v27, 31, v26
	v_cvt_pk_bf16_f32 v35, v41, v43
	v_cvt_pk_bf16_f32 v36, v45, v47
	v_cvt_pk_bf16_f32 v37, v49, v51
	v_lshlrev_b64 v[26:27], 11, v[26:27]
	ds_read2_b32 v[38:39], v30 offset0:49 offset1:57
	ds_read2_b32 v[40:41], v30 offset0:16 offset1:24
	ds_read2_b32 v[42:43], v30 offset0:82 offset1:90
	ds_read2_b32 v[44:45], v30 offset0:115 offset1:123
	ds_read2_b32 v[46:47], v30 offset0:148 offset1:156
	ds_read2_b32 v[48:49], v30 offset0:181 offset1:189
	ds_read2_b32 v[50:51], v30 offset0:214 offset1:222
	ds_read2_b32 v[54:55], v30 offset0:247 offset1:255
	v_lshl_add_u64 v[26:27], v[52:53], 0, v[26:27]
	global_store_dwordx4 v[26:27], v[34:37], off nt
	v_or_b32_e32 v26, s3, v32
	v_ashrrev_i32_e32 v27, 31, v26
	v_lshlrev_b64 v[26:27], 11, v[26:27]
	s_waitcnt lgkmcnt(6)
	v_cvt_pk_bf16_f32 v34, v40, v38
	s_waitcnt lgkmcnt(4)
	v_cvt_pk_bf16_f32 v35, v42, v44
	s_waitcnt lgkmcnt(2)
	v_cvt_pk_bf16_f32 v36, v46, v48
	s_waitcnt lgkmcnt(0)
	v_cvt_pk_bf16_f32 v37, v50, v54
	v_lshl_add_u64 v[26:27], v[52:53], 0, v[26:27]
	global_store_dwordx4 v[26:27], v[34:37], off nt
	v_or_b32_e32 v26, s3, v33
	v_ashrrev_i32_e32 v27, 31, v26
	v_lshlrev_b64 v[26:27], 11, v[26:27]
	v_cvt_pk_bf16_f32 v34, v41, v39
	v_cvt_pk_bf16_f32 v35, v43, v45
	v_cvt_pk_bf16_f32 v36, v47, v49
	v_cvt_pk_bf16_f32 v37, v51, v55
	v_lshl_add_u64 v[26:27], v[52:53], 0, v[26:27]
	global_store_dwordx4 v[26:27], v[34:37], off nt
	s_waitcnt lgkmcnt(0)
	s_branch .LBB0_227
